# speedup vs baseline: 1.0219x; 1.0068x over previous
; #define G_STAGE(bufoff, gbase) do { _Pragma("unroll") for (int _i = 0; _i < 2; ++_i) \
;     __builtin_amdgcn_global_load_lds((const unsigned*)((const char*)(gbase) + voffA[_i]), (LAS unsigned*)(lds + (bufoff) + ldsw + _i * 8192), 16, 0, 0); } while (0)
; #define G_LDA(dst, b, h) do { _Pragma("unroll") for (int m = 0; m < 4; ++m) _Pragma("unroll") for (int k = 0; k < 2; ++k) dst[m][k] = *(const LAS bf16x8*)(lds + G_SA(b, h) + aoff + m * 2048 + k * 1024); } while (0)
; #define G_LDB(dst, b, h) do { _Pragma("unroll") for (int n = 0; n < 2; ++n) _Pragma("unroll") for (int k = 0; k < 2; ++k) dst[n][k] = *(const LAS bf16x8*)(lds + G_SB(b, h) + boff + n * 2048 + k * 1024); } while (0)
; #define G_MMA(ai, bj, At, Bt) do { __builtin_amdgcn_s_setprio(1); _Pragma("unroll") for (int m = 0; m < 4; ++m) _Pragma("unroll") for (int n = 0; n < 2; ++n) _Pragma("unroll") for (int k = 0; k < 2; ++k) \
;     acc[ai][bj][m][n] = __builtin_amdgcn_mfma_f32_16x16x32_bf16(Bt[n][k], At[m][k], acc[ai][bj][m][n], 0, 0, 0); __builtin_amdgcn_s_setprio(0); } while (0)
; #define G_WAIT_V(n) asm volatile("s_waitcnt vmcnt(" #n ")" ::: "memory")
; #define G_WAIT_L(n) asm volatile("s_waitcnt lgkmcnt(" #n ")" ::: "memory")
; #define G_BAR __builtin_amdgcn_s_barrier()
; #define G_SCHED __builtin_amdgcn_sched_barrier(0)
; template <int MODE>
; __device__ __forceinline__ void gemm_phase(const Params& p, int layer, char* lds_generic) {
;     ...
;       G_LDB(B0, 0, 0); G_SCHED; G_LDA(At, 0, 0); G_STAGE(G_SA(1, 1), a1 + hstep);
;       G_WAIT_L(8); G_BAR; G_WAIT_L(0); G_MMA(0, 0, At, B0); G_BAR; G_SCHED;
;       G_LDB(B1, 0, 1); G_STAGE(G_SB(0, 0), b2);
;       G_BAR; G_WAIT_L(0); G_MMA(0, 1, At, B1); G_BAR;
;       G_LDA(At, 0, 1); G_STAGE(G_SA(0, 0), a2);
;       G_BAR; G_WAIT_L(0); G_MMA(1, 0, At, B0); G_BAR; G_SCHED;
;       G_STAGE(G_SB(0, 1), b2 + hstep);
;       G_WAIT_V(6); G_BAR; G_MMA(1, 1, At, B1); G_BAR;
;       G_LDB(B0, 1, 0); G_SCHED; G_LDA(At, 1, 0); G_STAGE(G_SA(0, 1), a2 + hstep);
;       G_WAIT_L(8); G_BAR; G_WAIT_L(0); G_MMA(0, 0, At, B0); G_BAR; G_SCHED;
.LBB0_196:
	v_or_b32_e32 v128, 0x10000, v152
	v_add_u32_e32 v132, 0x10400, v152
	v_add_u32_e32 v136, 0x10800, v152
	ds_read_b128 v[128:131], v128
	ds_read_b128 v[132:135], v132
	v_add_u32_e32 v137, 0x10c00, v152
	ds_read_b128 v[146:149], v136
	ds_read_b128 v[154:157], v137
	s_add_u32 s6, s4, 0xfff80080
	s_addc_u32 s7, s5, -1
	s_cmp_eq_u32 s47, 28
	s_cselect_b32 s9, s2, s7
	s_cselect_b32 s8, s21, s6
	s_cselect_b32 s7, s23, s46
	s_cselect_b32 s6, s34, s35
	v_lshl_add_u64 v[136:137], s[4:5], 0, v[142:143]
	s_add_i32 m0, s68, 0xc000
	ds_read_b128 v[158:161], v151
	ds_read_b128 v[162:165], v151 offset:1024
	ds_read_b128 v[166:169], v151 offset:2048
	ds_read_b128 v[170:173], v151 offset:3072
	ds_read_b128 v[174:177], v151 offset:4096
	ds_read_b128 v[178:181], v151 offset:5120
	ds_read_b128 v[182:185], v151 offset:6144
	ds_read_b128 v[186:189], v151 offset:7168
	global_load_lds_dwordx4 v[136:137], off
	v_lshl_add_u64 v[136:137], s[4:5], 0, v[144:145]
	s_add_i32 m0, s68, 0xe000
	s_nop 0
	global_load_lds_dwordx4 v[136:137], off
	s_waitcnt lgkmcnt(8)
	s_barrier
	s_waitcnt lgkmcnt(0)
	s_setprio 1
	s_waitcnt lgkmcnt(0)
	v_mfma_f32_16x16x32_bf16 v[124:127], v[128:131], v[158:161], v[124:127]
	v_mfma_f32_16x16x32_bf16 v[120:123], v[146:149], v[158:161], v[120:123]
	v_mfma_f32_16x16x32_bf16 v[108:111], v[128:131], v[166:169], v[108:111]
	v_mfma_f32_16x16x32_bf16 v[104:107], v[146:149], v[166:169], v[104:107]
	v_mfma_f32_16x16x32_bf16 v[92:95], v[128:131], v[174:177], v[92:95]
	v_mfma_f32_16x16x32_bf16 v[88:91], v[146:149], v[174:177], v[88:91]
	v_mfma_f32_16x16x32_bf16 v[76:79], v[128:131], v[182:185], v[76:79]
	v_mfma_f32_16x16x32_bf16 v[72:75], v[146:149], v[182:185], v[72:75]
	v_mfma_f32_16x16x32_bf16 v[124:127], v[132:135], v[162:165], v[124:127]
	v_mfma_f32_16x16x32_bf16 v[120:123], v[154:157], v[162:165], v[120:123]
	v_mfma_f32_16x16x32_bf16 v[108:111], v[132:135], v[170:173], v[108:111]
	v_mfma_f32_16x16x32_bf16 v[104:107], v[154:157], v[170:173], v[104:107]
	v_mfma_f32_16x16x32_bf16 v[92:95], v[132:135], v[178:181], v[92:95]
	v_mfma_f32_16x16x32_bf16 v[88:91], v[154:157], v[178:181], v[88:91]
	v_mfma_f32_16x16x32_bf16 v[76:79], v[132:135], v[186:189], v[76:79]
	v_mfma_f32_16x16x32_bf16 v[72:75], v[154:157], v[186:189], v[72:75]
	s_setprio 0
	s_barrier
	v_or_b32_e32 v136, 0x14000, v152
	v_add_u32_e32 v137, 0x14400, v152
	ds_read_b128 v[194:197], v136
	ds_read_b128 v[198:201], v137
	v_add_u32_e32 v136, 0x14800, v152
	v_add_u32_e32 v137, 0x14c00, v152
	s_mov_b32 m0, s69
	ds_read_b128 v[202:205], v136
	ds_read_b128 v[228:231], v137
	v_lshl_add_u64 v[136:137], s[6:7], 0, v[140:141]
	global_load_lds_dwordx4 v[136:137], off
	v_lshl_add_u64 v[190:191], s[6:7], 0, v[138:139]
	s_mov_b32 m0, s70
	s_nop 0
	global_load_lds_dwordx4 v[190:191], off
	s_barrier
	s_waitcnt lgkmcnt(0)
	s_setprio 1
	s_waitcnt lgkmcnt(0)
	v_mfma_f32_16x16x32_bf16 v[116:119], v[194:197], v[158:161], v[116:119]
	v_mfma_f32_16x16x32_bf16 v[112:115], v[202:205], v[158:161], v[112:115]
	v_mfma_f32_16x16x32_bf16 v[100:103], v[194:197], v[166:169], v[100:103]
	v_mfma_f32_16x16x32_bf16 v[96:99], v[202:205], v[166:169], v[96:99]
	v_mfma_f32_16x16x32_bf16 v[84:87], v[194:197], v[174:177], v[84:87]
	v_mfma_f32_16x16x32_bf16 v[80:83], v[202:205], v[174:177], v[80:83]
	v_mfma_f32_16x16x32_bf16 v[68:71], v[194:197], v[182:185], v[68:71]
	v_mfma_f32_16x16x32_bf16 v[64:67], v[202:205], v[182:185], v[64:67]
	v_mfma_f32_16x16x32_bf16 v[116:119], v[198:201], v[162:165], v[116:119]
	v_mfma_f32_16x16x32_bf16 v[112:115], v[228:231], v[162:165], v[112:115]
	v_mfma_f32_16x16x32_bf16 v[100:103], v[198:201], v[170:173], v[100:103]
	v_mfma_f32_16x16x32_bf16 v[96:99], v[228:231], v[170:173], v[96:99]
	v_mfma_f32_16x16x32_bf16 v[84:87], v[198:201], v[178:181], v[84:87]
	v_mfma_f32_16x16x32_bf16 v[80:83], v[228:231], v[178:181], v[80:83]
	v_mfma_f32_16x16x32_bf16 v[68:71], v[198:201], v[186:189], v[68:71]
	v_mfma_f32_16x16x32_bf16 v[64:67], v[228:231], v[186:189], v[64:67]
	s_setprio 0
	s_mov_b32 m0, s68
	v_lshl_add_u64 v[206:207], s[8:9], 0, v[140:141]
	s_barrier
	ds_read_b128 v[158:161], v151 offset:16384
	ds_read_b128 v[162:165], v151 offset:17408
	ds_read_b128 v[166:169], v151 offset:18432
	ds_read_b128 v[170:173], v151 offset:19456
	ds_read_b128 v[174:177], v151 offset:20480
	ds_read_b128 v[178:181], v151 offset:21504
	ds_read_b128 v[182:185], v151 offset:22528
	ds_read_b128 v[186:189], v151 offset:23552
	global_load_lds_dwordx4 v[206:207], off
	v_lshl_add_u64 v[208:209], s[8:9], 0, v[138:139]
	s_mov_b32 m0, s71
	s_nop 0
	global_load_lds_dwordx4 v[208:209], off
	s_barrier
	s_waitcnt lgkmcnt(0)
	s_setprio 1
	s_waitcnt lgkmcnt(0)
	v_mfma_f32_16x16x32_bf16 v[60:63], v[128:131], v[158:161], v[60:63]
	v_mfma_f32_16x16x32_bf16 v[56:59], v[146:149], v[158:161], v[56:59]
	v_mfma_f32_16x16x32_bf16 v[44:47], v[128:131], v[166:169], v[44:47]
	v_mfma_f32_16x16x32_bf16 v[40:43], v[146:149], v[166:169], v[40:43]
	v_mfma_f32_16x16x32_bf16 v[28:31], v[128:131], v[174:177], v[28:31]
	v_mfma_f32_16x16x32_bf16 v[24:27], v[146:149], v[174:177], v[24:27]
	v_mfma_f32_16x16x32_bf16 v[12:15], v[128:131], v[182:185], v[12:15]
	v_mfma_f32_16x16x32_bf16 v[8:11], v[146:149], v[182:185], v[8:11]
	v_mfma_f32_16x16x32_bf16 v[60:63], v[132:135], v[162:165], v[60:63]
	v_mfma_f32_16x16x32_bf16 v[56:59], v[154:157], v[162:165], v[56:59]
	v_mfma_f32_16x16x32_bf16 v[44:47], v[132:135], v[170:173], v[44:47]
	v_mfma_f32_16x16x32_bf16 v[40:43], v[154:157], v[170:173], v[40:43]
	v_mfma_f32_16x16x32_bf16 v[28:31], v[132:135], v[178:181], v[28:31]
	v_mfma_f32_16x16x32_bf16 v[24:27], v[154:157], v[178:181], v[24:27]
	v_mfma_f32_16x16x32_bf16 v[12:15], v[132:135], v[186:189], v[12:15]
	v_mfma_f32_16x16x32_bf16 v[8:11], v[154:157], v[186:189], v[8:11]
	s_setprio 0
	s_barrier
; #define G_STAGE(bufoff, gbase) do { _Pragma("unroll") for (int _i = 0; _i < 2; ++_i) \
;     __builtin_amdgcn_global_load_lds((const unsigned*)((const char*)(gbase) + voffA[_i]), (LAS unsigned*)(lds + (bufoff) + ldsw + _i * 8192), 16, 0, 0); } while (0)
; #define G_LDA(dst, b, h) do { _Pragma("unroll") for (int m = 0; m < 4; ++m) _Pragma("unroll") for (int k = 0; k < 2; ++k) dst[m][k] = *(const LAS bf16x8*)(lds + G_SA(b, h) + aoff + m * 2048 + k * 1024); } while (0)
; #define G_LDB(dst, b, h) do { _Pragma("unroll") for (int n = 0; n < 2; ++n) _Pragma("unroll") for (int k = 0; k < 2; ++k) dst[n][k] = *(const LAS bf16x8*)(lds + G_SB(b, h) + boff + n * 2048 + k * 1024); } while (0)
; #define G_MMA(ai, bj, At, Bt) do { __builtin_amdgcn_s_setprio(1); _Pragma("unroll") for (int m = 0; m < 4; ++m) _Pragma("unroll") for (int n = 0; n < 2; ++n) _Pragma("unroll") for (int k = 0; k < 2; ++k) \
;     acc[ai][bj][m][n] = __builtin_amdgcn_mfma_f32_16x16x32_bf16(Bt[n][k], At[m][k], acc[ai][bj][m][n], 0, 0, 0); __builtin_amdgcn_s_setprio(0); } while (0)
; #define G_WAIT_V(n) asm volatile("s_waitcnt vmcnt(" #n ")" ::: "memory")
; #define G_WAIT_L(n) asm volatile("s_waitcnt lgkmcnt(" #n ")" ::: "memory")
; #define G_BAR __builtin_amdgcn_s_barrier()
; #define G_SCHED __builtin_amdgcn_sched_barrier(0)
; template <int MODE>
; __device__ __forceinline__ void gemm_phase(const Params& p, int layer, char* lds_generic) {
;     ...
;       G_WAIT_V(6); G_BAR; G_MMA(1, 1, At, B1); G_BAR;
;       G_LDB(B0, 1, 0); G_SCHED; G_LDA(At, 1, 0); G_STAGE(G_SA(0, 1), a2 + hstep);
;       G_WAIT_L(8); G_BAR; G_WAIT_L(0); G_MMA(0, 0, At, B0); G_BAR; G_SCHED;
;       G_LDB(B1, 1, 1); G_STAGE(G_SB(1, 0), b3);
;       G_BAR; G_WAIT_L(0); G_MMA(0, 1, At, B1); G_BAR;
;       G_LDA(At, 1, 1); G_STAGE(G_SA(1, 0), a3);
;       G_BAR; G_WAIT_L(0); G_MMA(1, 0, At, B0); G_BAR; G_SCHED;
;       G_STAGE(G_SB(1, 1), b3 + hstep);
	s_add_u32 s48, s6, 0x80000
	s_addc_u32 s49, s7, 0
	s_mov_b32 m0, s72
	v_lshl_add_u64 v[128:129], s[48:49], 0, v[140:141]
	global_load_lds_dwordx4 v[128:129], off
	v_lshl_add_u64 v[128:129], s[48:49], 0, v[138:139]
	s_mov_b32 m0, s73
	s_nop 0
	global_load_lds_dwordx4 v[128:129], off
	s_waitcnt vmcnt(6)
	s_barrier
	s_setprio 1
	v_mfma_f32_16x16x32_bf16 v[52:55], v[194:197], v[158:161], v[52:55]
	v_mfma_f32_16x16x32_bf16 v[48:51], v[202:205], v[158:161], v[48:51]
	v_mfma_f32_16x16x32_bf16 v[36:39], v[194:197], v[166:169], v[36:39]
	v_mfma_f32_16x16x32_bf16 v[32:35], v[202:205], v[166:169], v[32:35]
	v_mfma_f32_16x16x32_bf16 v[20:23], v[194:197], v[174:177], v[20:23]
	v_mfma_f32_16x16x32_bf16 v[16:19], v[202:205], v[174:177], v[16:19]
	v_mfma_f32_16x16x32_bf16 v[4:7], v[194:197], v[182:185], v[4:7]
	v_mfma_f32_16x16x32_bf16 v[0:3], v[202:205], v[182:185], v[0:3]
	v_mfma_f32_16x16x32_bf16 v[52:55], v[198:201], v[162:165], v[52:55]
	v_mfma_f32_16x16x32_bf16 v[48:51], v[228:231], v[162:165], v[48:51]
	v_mfma_f32_16x16x32_bf16 v[36:39], v[198:201], v[170:173], v[36:39]
	v_mfma_f32_16x16x32_bf16 v[32:35], v[228:231], v[170:173], v[32:35]
	v_mfma_f32_16x16x32_bf16 v[20:23], v[198:201], v[178:181], v[20:23]
	v_mfma_f32_16x16x32_bf16 v[16:19], v[228:231], v[178:181], v[16:19]
	v_mfma_f32_16x16x32_bf16 v[4:7], v[198:201], v[186:189], v[4:7]
	v_mfma_f32_16x16x32_bf16 v[0:3], v[228:231], v[186:189], v[0:3]
	s_setprio 0
	v_or_b32_e32 v128, 0x18000, v152
	v_add_u32_e32 v132, 0x18400, v152
	v_add_u32_e32 v146, 0x18800, v152
	v_add_u32_e32 v154, 0x18c00, v152
	s_barrier
	ds_read_b128 v[128:131], v128
	ds_read_b128 v[132:135], v132
	ds_read_b128 v[146:149], v146
	ds_read_b128 v[154:157], v154
	s_add_u32 s8, s8, 0x80000
	s_addc_u32 s9, s9, 0
	s_mov_b32 m0, s74
	v_lshl_add_u64 v[194:195], s[8:9], 0, v[140:141]
	ds_read_b128 v[158:161], v151 offset:32768
	ds_read_b128 v[162:165], v151 offset:33792
	ds_read_b128 v[166:169], v151 offset:34816
	ds_read_b128 v[170:173], v151 offset:35840
	ds_read_b128 v[174:177], v151 offset:36864
	ds_read_b128 v[178:181], v151 offset:37888
	ds_read_b128 v[182:185], v151 offset:38912
	ds_read_b128 v[186:189], v151 offset:39936
	global_load_lds_dwordx4 v[194:195], off
	v_lshl_add_u64 v[194:195], s[8:9], 0, v[138:139]
	s_mov_b32 m0, s75
	s_nop 0
	global_load_lds_dwordx4 v[194:195], off
	s_waitcnt lgkmcnt(8)
	s_barrier
	s_waitcnt lgkmcnt(0)
	s_setprio 1
	s_waitcnt lgkmcnt(0)
	v_mfma_f32_16x16x32_bf16 v[124:127], v[128:131], v[158:161], v[124:127]
	v_mfma_f32_16x16x32_bf16 v[120:123], v[146:149], v[158:161], v[120:123]
	v_mfma_f32_16x16x32_bf16 v[108:111], v[128:131], v[166:169], v[108:111]
	v_mfma_f32_16x16x32_bf16 v[104:107], v[146:149], v[166:169], v[104:107]
	v_mfma_f32_16x16x32_bf16 v[92:95], v[128:131], v[174:177], v[92:95]
	v_mfma_f32_16x16x32_bf16 v[88:91], v[146:149], v[174:177], v[88:91]
	v_mfma_f32_16x16x32_bf16 v[76:79], v[128:131], v[182:185], v[76:79]
	v_mfma_f32_16x16x32_bf16 v[72:75], v[146:149], v[182:185], v[72:75]
	v_mfma_f32_16x16x32_bf16 v[124:127], v[132:135], v[162:165], v[124:127]
	v_mfma_f32_16x16x32_bf16 v[120:123], v[154:157], v[162:165], v[120:123]
	v_mfma_f32_16x16x32_bf16 v[108:111], v[132:135], v[170:173], v[108:111]
	v_mfma_f32_16x16x32_bf16 v[104:107], v[154:157], v[170:173], v[104:107]
	v_mfma_f32_16x16x32_bf16 v[92:95], v[132:135], v[178:181], v[92:95]
	v_mfma_f32_16x16x32_bf16 v[88:91], v[154:157], v[178:181], v[88:91]
	v_mfma_f32_16x16x32_bf16 v[76:79], v[132:135], v[186:189], v[76:79]
	v_mfma_f32_16x16x32_bf16 v[72:75], v[154:157], v[186:189], v[72:75]
	s_setprio 0
	s_barrier
	s_mov_b32 m0, s77
	v_or_b32_e32 v194, 0x1c000, v152
	v_add_u32_e32 v198, 0x1c400, v152
	v_add_u32_e32 v202, 0x1c800, v152
	v_lshl_add_u64 v[136:137], v[136:137], 0, s[90:91]
	ds_read_b128 v[194:197], v194
	ds_read_b128 v[198:201], v198
	v_add_u32_e32 v210, 0x1cc00, v152
	ds_read_b128 v[202:205], v202
	ds_read_b128 v[228:231], v210
	global_load_lds_dwordx4 v[136:137], off
	v_lshl_add_u64 v[136:137], v[190:191], 0, s[90:91]
	s_mov_b32 m0, s78
	s_nop 0
	global_load_lds_dwordx4 v[136:137], off
	s_barrier
	s_waitcnt lgkmcnt(0)
	s_setprio 1
	s_waitcnt lgkmcnt(0)
	v_mfma_f32_16x16x32_bf16 v[116:119], v[194:197], v[158:161], v[116:119]
	v_mfma_f32_16x16x32_bf16 v[112:115], v[202:205], v[158:161], v[112:115]
	v_mfma_f32_16x16x32_bf16 v[100:103], v[194:197], v[166:169], v[100:103]
	v_mfma_f32_16x16x32_bf16 v[96:99], v[202:205], v[166:169], v[96:99]
	v_mfma_f32_16x16x32_bf16 v[84:87], v[194:197], v[174:177], v[84:87]
	v_mfma_f32_16x16x32_bf16 v[80:83], v[202:205], v[174:177], v[80:83]
	v_mfma_f32_16x16x32_bf16 v[68:71], v[194:197], v[182:185], v[68:71]
	v_mfma_f32_16x16x32_bf16 v[64:67], v[202:205], v[182:185], v[64:67]
	v_mfma_f32_16x16x32_bf16 v[116:119], v[198:201], v[162:165], v[116:119]
	v_mfma_f32_16x16x32_bf16 v[112:115], v[228:231], v[162:165], v[112:115]
	v_mfma_f32_16x16x32_bf16 v[100:103], v[198:201], v[170:173], v[100:103]
	v_mfma_f32_16x16x32_bf16 v[96:99], v[228:231], v[170:173], v[96:99]
	v_mfma_f32_16x16x32_bf16 v[84:87], v[198:201], v[178:181], v[84:87]
	v_mfma_f32_16x16x32_bf16 v[80:83], v[228:231], v[178:181], v[80:83]
	v_mfma_f32_16x16x32_bf16 v[68:71], v[198:201], v[186:189], v[68:71]
	v_mfma_f32_16x16x32_bf16 v[64:67], v[228:231], v[186:189], v[64:67]
	s_setprio 0
	s_mov_b32 m0, s79
	v_lshl_add_u64 v[136:137], v[206:207], 0, s[90:91]
	s_barrier
	ds_read_b128 v[158:161], v151 offset:49152
	ds_read_b128 v[162:165], v151 offset:50176
	ds_read_b128 v[166:169], v151 offset:51200
	ds_read_b128 v[170:173], v151 offset:52224
	ds_read_b128 v[174:177], v151 offset:53248
	ds_read_b128 v[178:181], v151 offset:54272
	ds_read_b128 v[182:185], v151 offset:55296
	ds_read_b128 v[186:189], v151 offset:56320
	global_load_lds_dwordx4 v[136:137], off
	v_lshl_add_u64 v[136:137], v[208:209], 0, s[90:91]
	s_mov_b32 m0, s86
	s_nop 0
	global_load_lds_dwordx4 v[136:137], off
	s_barrier
;   __device__ __forceinline__ bf16_t* Z() const { return (bf16_t*)(ws + 456 * MB); }
;   __device__ __forceinline__ float* cosT() const { return (float*)(ws + 904 * MB); }
;   __device__ __forceinline__ float* sinT() const { return (float*)(ws + 905 * MB); }
;   __device__ __forceinline__ float* RS() const { return (float*)(ws + 906 * MB); }
; #define G_STAGE(bufoff, gbase) do { _Pragma("unroll") for (int _i = 0; _i < 2; ++_i) \
;     __builtin_amdgcn_global_load_lds((const unsigned*)((const char*)(gbase) + voffA[_i]), (LAS unsigned*)(lds + (bufoff) + ldsw + _i * 8192), 16, 0, 0); } while (0)
; #define G_WAIT_V(n) asm volatile("s_waitcnt vmcnt(" #n ")" ::: "memory")
; template <int MODE>
; __device__ __forceinline__ void gemm_epilogue(const Params& p, int layer, const f32x4 (&acc)[2][2][4][2], int pm, int pn, int wr, int wc, int fr, int fq) {
;     ...
;       const int row = pm * 256 + ai * 128 + wr * 64 + m * 16 + fr;
;       if (MODE == 0) {
;         const float rsv = p.RS()[row];
;         const int pos = (row < NPROMPT) ? (row & 8191) : (row & 4095);
; #pragma unroll
;         for (int bj = 0; bj < 2; ++bj) {
;           const int colt = pn * 256 + bj * 128 + wc * 32;
;           f32x4 v0 = acc[ai][bj][m][0] * rsv, v1 = acc[ai][bj][m][1] * rsv;
;           bf16_t* zp = p.Z() + (size_t)row * LDZ + colt;
;           if (colt < 2048) {
;             const int ti = pos * 32 + 16 * (wc & 1) + 4 * fq;
;             const f32x4 c = *(const f32x4*)(p.cosT() + ti), s = *(const f32x4*)(p.sinT() + ti);
;             const float qs = (colt < 1024) ? 0.18033688011112042f : 1.f;
;             const f32x4 o0 = (v0 * c - v1 * s) * qs, o1 = (v1 * c + v0 * s) * qs;
;             const u32x4 w = {cvtpk(o0[0], o0[1]), cvtpk(o0[2], o0[3]), cvtpk(o1[0], o1[1]), cvtpk(o1[2], o1[3])};
;             *(u32x4*)(zp + 8 * fq) = w;
;           } else {
;             if (colt >= 3072) {
; #pragma unroll
;               for (int e = 0; e < 4; ++e) { v0[e] = gelu_tanh(v0[e]); v1[e] = gelu_tanh(v1[e]); }
; template <int MODE>
; __device__ __forceinline__ void gemm_phase(const Params& p, int layer, char* lds_generic) {
;     ...
;       G_BAR; G_WAIT_L(0); G_MMA(0, 1, At, B1); G_BAR;
;       G_LDA(At, 1, 1); G_STAGE(G_SA(1, 0), a3);
;       G_BAR; G_WAIT_L(0); G_MMA(1, 0, At, B0); G_BAR; G_SCHED;
;       G_STAGE(G_SB(1, 1), b3 + hstep);
;       G_WAIT_V(6); G_BAR; G_MMA(1, 1, At, B1); G_BAR;
	s_waitcnt lgkmcnt(0)
	s_setprio 1
	s_waitcnt lgkmcnt(0)
	v_mfma_f32_16x16x32_bf16 v[60:63], v[128:131], v[158:161], v[60:63]
	v_mfma_f32_16x16x32_bf16 v[56:59], v[146:149], v[158:161], v[56:59]
	v_mfma_f32_16x16x32_bf16 v[44:47], v[128:131], v[166:169], v[44:47]
	v_mfma_f32_16x16x32_bf16 v[40:43], v[146:149], v[166:169], v[40:43]
	v_mfma_f32_16x16x32_bf16 v[28:31], v[128:131], v[174:177], v[28:31]
	v_mfma_f32_16x16x32_bf16 v[24:27], v[146:149], v[174:177], v[24:27]
	v_mfma_f32_16x16x32_bf16 v[12:15], v[128:131], v[182:185], v[12:15]
	v_mfma_f32_16x16x32_bf16 v[8:11], v[146:149], v[182:185], v[8:11]
	v_mfma_f32_16x16x32_bf16 v[60:63], v[132:135], v[162:165], v[60:63]
	v_mfma_f32_16x16x32_bf16 v[56:59], v[154:157], v[162:165], v[56:59]
	v_mfma_f32_16x16x32_bf16 v[44:47], v[132:135], v[170:173], v[44:47]
	v_mfma_f32_16x16x32_bf16 v[40:43], v[154:157], v[170:173], v[40:43]
	v_mfma_f32_16x16x32_bf16 v[28:31], v[132:135], v[178:181], v[28:31]
	v_mfma_f32_16x16x32_bf16 v[24:27], v[154:157], v[178:181], v[24:27]
	v_mfma_f32_16x16x32_bf16 v[12:15], v[132:135], v[186:189], v[12:15]
	v_mfma_f32_16x16x32_bf16 v[8:11], v[154:157], v[186:189], v[8:11]
	s_setprio 0
	s_barrier
	s_add_u32 s6, s6, 0x80080
	s_addc_u32 s7, s7, 0
	s_mov_b32 m0, s87
	v_lshl_add_u64 v[128:129], s[6:7], 0, v[140:141]
	global_load_lds_dwordx4 v[128:129], off
	v_lshl_add_u64 v[128:129], s[6:7], 0, v[138:139]
	s_mov_b32 m0, s88
	s_nop 0
	global_load_lds_dwordx4 v[128:129], off
	s_waitcnt vmcnt(6)
	s_barrier
	s_setprio 1
	v_mfma_f32_16x16x32_bf16 v[52:55], v[194:197], v[158:161], v[52:55]
	v_mfma_f32_16x16x32_bf16 v[48:51], v[202:205], v[158:161], v[48:51]
	v_mfma_f32_16x16x32_bf16 v[36:39], v[194:197], v[166:169], v[36:39]
	v_mfma_f32_16x16x32_bf16 v[32:35], v[202:205], v[166:169], v[32:35]
	v_mfma_f32_16x16x32_bf16 v[20:23], v[194:197], v[174:177], v[20:23]
	v_mfma_f32_16x16x32_bf16 v[16:19], v[202:205], v[174:177], v[16:19]
	v_mfma_f32_16x16x32_bf16 v[4:7], v[194:197], v[182:185], v[4:7]
	v_mfma_f32_16x16x32_bf16 v[0:3], v[202:205], v[182:185], v[0:3]
	v_mfma_f32_16x16x32_bf16 v[52:55], v[198:201], v[162:165], v[52:55]
	v_mfma_f32_16x16x32_bf16 v[48:51], v[228:231], v[162:165], v[48:51]
	v_mfma_f32_16x16x32_bf16 v[36:39], v[198:201], v[170:173], v[36:39]
	v_mfma_f32_16x16x32_bf16 v[32:35], v[228:231], v[170:173], v[32:35]
	v_mfma_f32_16x16x32_bf16 v[20:23], v[198:201], v[178:181], v[20:23]
	v_mfma_f32_16x16x32_bf16 v[16:19], v[228:231], v[178:181], v[16:19]
	v_mfma_f32_16x16x32_bf16 v[4:7], v[198:201], v[186:189], v[4:7]
	v_mfma_f32_16x16x32_bf16 v[0:3], v[228:231], v[186:189], v[0:3]
	s_setprio 0
	s_add_i32 s47, s47, 2
	s_add_u32 s4, s4, 0x100
	s_addc_u32 s5, s5, 0
	s_add_u32 s35, s35, 0x100
	s_addc_u32 s46, s46, 0
	s_cmp_gt_u32 s47, 29
	s_barrier
	s_cbranch_scc0 .LBB0_196
	v_lshl_add_u32 v146, s1, 8, v150
	v_ashrrev_i32_e32 v147, 31, v146
	v_lshl_add_u64 v[128:129], v[146:147], 2, s[12:13]
	global_load_dword v148, v[128:129], off
	global_load_dword v243, v[128:129], off offset:64
	global_load_dword v244, v[128:129], off offset:128
	global_load_dword v245, v[128:129], off offset:192
	global_load_dword v246, v[128:129], off offset:512
	global_load_dword v247, v[128:129], off offset:576
	global_load_dword v248, v[128:129], off offset:640
	global_load_dword v249, v[128:129], off offset:704
	s_lshl_b32 s1, s33, 8
	s_or_b32 s46, s1, s76
	s_cmpk_gt_i32 s46, 0x7ff
	s_movk_i32 s2, 0x4000
	s_cselect_b64 s[8:9], -1, 0
	v_cmp_gt_i32_e64 s[4:5], s2, v146
	s_mov_b64 s[6:7], -1
	s_and_b64 vcc, exec, s[8:9]
	s_waitcnt vmcnt(0)
	v_pk_mul_f32 v[126:127], v[126:127], v[148:149] op_sel_hi:[1,0]
	v_pk_mul_f32 v[124:125], v[124:125], v[148:149] op_sel_hi:[1,0]
	v_pk_mul_f32 v[122:123], v[122:123], v[148:149] op_sel_hi:[1,0]
	v_pk_mul_f32 v[120:121], v[120:121], v[148:149] op_sel_hi:[1,0]
	s_cbranch_vccz .LBB0_201
	v_mov_b64_e32 v[132:133], v[122:123]
	v_mov_b64_e32 v[136:137], v[126:127]
	s_cmpk_lt_u32 s1, 0xc00
	v_mov_b64_e32 v[130:131], v[120:121]
	v_mov_b64_e32 v[134:135], v[124:125]
	s_cbranch_scc1 .LBB0_200
	v_mul_f32_e32 v129, v120, v120
	v_fmamk_f32 v129, v129, 0x3dd2d3e8, v214
	v_mul_f32_e32 v130, v125, v125
	v_mul_f32_e64 v129, v120, -v129
	v_fmamk_f32 v130, v130, 0x3dd2d3e8, v214
	v_exp_f32_e32 v129, v129
	v_mul_f32_e64 v130, v125, -v130
	v_exp_f32_e32 v131, v130
	v_mul_f32_e32 v133, v122, v122
	v_add_f32_e32 v129, 1.0, v129
	v_mul_f32_e32 v128, v124, v124
	v_rcp_f32_e32 v130, v129
	v_add_f32_e32 v129, 1.0, v131
	v_mul_f32_e32 v131, v121, v121
	v_mul_f32_e32 v132, v126, v126
	v_fmamk_f32 v133, v133, 0x3dd2d3e8, v214
	v_mul_f32_e32 v134, v127, v127
	v_mul_f32_e32 v135, v123, v123
	v_fmamk_f32 v128, v128, 0x3dd2d3e8, v214
	v_fmamk_f32 v131, v131, 0x3dd2d3e8, v214
	v_fmamk_f32 v132, v132, 0x3dd2d3e8, v214
	v_mul_f32_e64 v133, v122, -v133
	v_fmamk_f32 v134, v134, 0x3dd2d3e8, v214
	v_fmamk_f32 v135, v135, 0x3dd2d3e8, v214
	v_mul_f32_e64 v128, v124, -v128
	v_mul_f32_e64 v131, v121, -v131
	v_mul_f32_e64 v132, v126, -v132
	v_exp_f32_e32 v133, v133
	v_mul_f32_e64 v134, v127, -v134
	v_mul_f32_e64 v135, v123, -v135
	v_exp_f32_e32 v128, v128
	v_exp_f32_e32 v131, v131
	v_exp_f32_e32 v132, v132
	v_exp_f32_e32 v134, v134
	v_exp_f32_e32 v135, v135
	v_add_f32_e32 v133, 1.0, v133
	v_add_f32_e32 v128, 1.0, v128
	v_add_f32_e32 v131, 1.0, v131
	v_add_f32_e32 v132, 1.0, v132
	v_rcp_f32_e32 v154, v133
	v_add_f32_e32 v133, 1.0, v134
	v_add_f32_e32 v134, 1.0, v135
	v_rcp_f32_e32 v128, v128
	v_rcp_f32_e32 v129, v129
	v_rcp_f32_e32 v132, v132
	v_rcp_f32_e32 v133, v133
	v_rcp_f32_e32 v155, v134
	v_rcp_f32_e32 v131, v131
	v_pk_mul_f32 v[134:135], v[124:125], v[128:129]
	v_pk_mul_f32 v[136:137], v[126:127], v[132:133]
	v_pk_mul_f32 v[132:133], v[122:123], v[154:155]
	v_pk_mul_f32 v[130:131], v[120:121], v[130:131]

;   __device__ __forceinline__ bf16_t* Z() const { return (bf16_t*)(ws + 456 * MB); }
;   __device__ __forceinline__ float* cosT() const { return (float*)(ws + 904 * MB); }
;   __device__ __forceinline__ float* sinT() const { return (float*)(ws + 905 * MB); }
; template <int MODE>
; __device__ __forceinline__ void gemm_epilogue(const Params& p, int layer, const f32x4 (&acc)[2][2][4][2], int pm, int pn, int wr, int wc, int fr, int fq) {
;     ...
;         const int pos = (row < NPROMPT) ? (row & 8191) : (row & 4095);
; #pragma unroll
;         for (int bj = 0; bj < 2; ++bj) {
;           const int colt = pn * 256 + bj * 128 + wc * 32;
;           f32x4 v0 = acc[ai][bj][m][0] * rsv, v1 = acc[ai][bj][m][1] * rsv;
;           bf16_t* zp = p.Z() + (size_t)row * LDZ + colt;
;           if (colt < 2048) {
;             const int ti = pos * 32 + 16 * (wc & 1) + 4 * fq;
;             const f32x4 c = *(const f32x4*)(p.cosT() + ti), s = *(const f32x4*)(p.sinT() + ti);
;             const float qs = (colt < 1024) ? 0.18033688011112042f : 1.f;
;             const f32x4 o0 = (v0 * c - v1 * s) * qs, o1 = (v1 * c + v0 * s) * qs;
;             const u32x4 w = {cvtpk(o0[0], o0[1]), cvtpk(o0[2], o0[3]), cvtpk(o1[0], o1[1]), cvtpk(o1[2], o1[3])};
;             *(u32x4*)(zp + 8 * fq) = w;
.LBB0_201:
	v_cndmask_b32_e64 v132, v253, v237, s[4:5]
	v_and_b32_e32 v132, v132, v146
	v_lshl_or_b32 v132, v132, 5, v153
	s_ashr_i32 s47, s46, 31
	s_and_b64 vcc, exec, s[6:7]
	v_lshlrev_b32_e32 v134, 2, v132
	s_cbranch_vccz .LBB0_203
	global_load_dwordx4 v[128:131], v134, s[18:19]
	global_load_dwordx4 v[154:157], v134, s[16:17]
	s_cmpk_lt_i32 s46, 0x400
	s_cselect_b64 vcc, -1, 0
	v_cndmask_b32_e32 v132, 1.0, v220, vcc
	s_waitcnt vmcnt(0)
	v_mov_b64_e32 v[216:217], v[128:129]
	v_mov_b64_e32 v[218:219], v[130:131]
	v_mov_b64_e32 v[222:223], v[154:155]
	v_mov_b64_e32 v[224:225], v[156:157]
	v_pk_mul_f32 v[136:137], v[122:123], v[130:131]
	v_pk_mul_f32 v[158:159], v[120:121], v[128:129]
	v_pk_mul_f32 v[130:131], v[126:127], v[130:131]
	v_pk_mul_f32 v[128:129], v[124:125], v[128:129]
	v_pk_fma_f32 v[126:127], v[126:127], v[156:157], v[136:137] neg_lo:[0,0,1] neg_hi:[0,0,1]
	v_pk_fma_f32 v[124:125], v[124:125], v[154:155], v[158:159] neg_lo:[0,0,1] neg_hi:[0,0,1]
	v_pk_fma_f32 v[122:123], v[122:123], v[156:157], v[130:131]
	v_pk_fma_f32 v[120:121], v[120:121], v[154:155], v[128:129]
	v_pk_mul_f32 v[126:127], v[132:133], v[126:127] op_sel_hi:[0,1]
	v_pk_mul_f32 v[124:125], v[132:133], v[124:125] op_sel_hi:[0,1]
	v_pk_mul_f32 v[122:123], v[132:133], v[122:123] op_sel_hi:[0,1]
	v_pk_mul_f32 v[120:121], v[132:133], v[120:121] op_sel_hi:[0,1]
	v_cvt_pk_bf16_f32 v128, v124, v125
	v_cvt_pk_bf16_f32 v129, v126, v127
	v_cvt_pk_bf16_f32 v130, v120, v121
	v_cvt_pk_bf16_f32 v131, v122, v123

;   __device__ __forceinline__ bf16_t* Z() const { return (bf16_t*)(ws + 456 * MB); }
;   __device__ __forceinline__ float* cosT() const { return (float*)(ws + 904 * MB); }
;   __device__ __forceinline__ float* sinT() const { return (float*)(ws + 905 * MB); }
;   __device__ __forceinline__ float* RS() const { return (float*)(ws + 906 * MB); }
; template <int MODE>
; __device__ __forceinline__ void gemm_epilogue(const Params& p, int layer, const f32x4 (&acc)[2][2][4][2], int pm, int pn, int wr, int wc, int fr, int fq) {
;     ...
;       const int row = pm * 256 + ai * 128 + wr * 64 + m * 16 + fr;
;       if (MODE == 0) {
;         const float rsv = p.RS()[row];
;         const int pos = (row < NPROMPT) ? (row & 8191) : (row & 4095);
; #pragma unroll
;         for (int bj = 0; bj < 2; ++bj) {
;           const int colt = pn * 256 + bj * 128 + wc * 32;
;           f32x4 v0 = acc[ai][bj][m][0] * rsv, v1 = acc[ai][bj][m][1] * rsv;
;           bf16_t* zp = p.Z() + (size_t)row * LDZ + colt;
;           if (colt < 2048) {
;             const int ti = pos * 32 + 16 * (wc & 1) + 4 * fq;
;             const f32x4 c = *(const f32x4*)(p.cosT() + ti), s = *(const f32x4*)(p.sinT() + ti);
;             const float qs = (colt < 1024) ? 0.18033688011112042f : 1.f;
;             const f32x4 o0 = (v0 * c - v1 * s) * qs, o1 = (v1 * c + v0 * s) * qs;
;             const u32x4 w = {cvtpk(o0[0], o0[1]), cvtpk(o0[2], o0[3]), cvtpk(o1[0], o1[1]), cvtpk(o1[2], o1[3])};
;             *(u32x4*)(zp + 8 * fq) = w;
;           } else {
;             if (colt >= 3072) {
; #pragma unroll
;               for (int e = 0; e < 4; ++e) { v0[e] = gelu_tanh(v0[e]); v1[e] = gelu_tanh(v1[e]); }
;             }
;             const u32x4 w = {cvtpk(v0[0], v0[1]), cvtpk(v0[2], v0[3]), cvtpk(v1[0], v1[1]), cvtpk(v1[2], v1[3])};
;             *(u32x4*)(zp + 8 * fq) = w;
.LBB0_207:
	s_and_b64 vcc, exec, s[4:5]
	s_cbranch_vccz .LBB0_209
	v_mov_b64_e32 v[120:121], v[216:217]
	v_mov_b64_e32 v[122:123], v[218:219]
	v_mov_b64_e32 v[124:125], v[222:223]
	v_mov_b64_e32 v[126:127], v[224:225]
	s_cmpk_lt_i32 s21, 0x400
	s_cselect_b64 vcc, -1, 0
	v_cndmask_b32_e32 v128, 1.0, v220, vcc
	v_pk_mul_f32 v[130:131], v[114:115], v[122:123]
	v_pk_mul_f32 v[134:135], v[112:113], v[120:121]
	v_pk_mul_f32 v[122:123], v[118:119], v[122:123]
	v_pk_mul_f32 v[120:121], v[116:117], v[120:121]
	v_pk_fma_f32 v[118:119], v[118:119], v[126:127], v[130:131] neg_lo:[0,0,1] neg_hi:[0,0,1]
	v_pk_fma_f32 v[116:117], v[116:117], v[124:125], v[134:135] neg_lo:[0,0,1] neg_hi:[0,0,1]
	v_pk_fma_f32 v[114:115], v[114:115], v[126:127], v[122:123]
	v_pk_fma_f32 v[112:113], v[112:113], v[124:125], v[120:121]
	v_pk_mul_f32 v[118:119], v[128:129], v[118:119] op_sel_hi:[0,1]
	v_pk_mul_f32 v[116:117], v[128:129], v[116:117] op_sel_hi:[0,1]
	v_pk_mul_f32 v[114:115], v[128:129], v[114:115] op_sel_hi:[0,1]
	v_pk_mul_f32 v[112:113], v[128:129], v[112:113] op_sel_hi:[0,1]
	v_cvt_pk_bf16_f32 v120, v116, v117
	v_cvt_pk_bf16_f32 v121, v118, v119
	v_cvt_pk_bf16_f32 v122, v112, v113
	v_cvt_pk_bf16_f32 v123, v114, v115
.LBB0_209:
	v_or_b32_e32 v124, 16, v146
	v_ashrrev_i32_e32 v125, 31, v124
	global_store_dwordx4 v[132:133], v[120:123], off offset:256
	v_lshl_add_u64 v[112:113], v[124:125], 2, s[12:13]
	v_cndmask_b32_e64 v112, 0, 1, s[8:9]
	v_cmp_gt_i32_e64 s[6:7], s2, v124
	v_cmp_ne_u32_e64 s[4:5], 1, v112
	s_andn2_b64 vcc, exec, s[8:9]
	s_mov_b64 s[8:9], -1
	v_mov_b32_e32 v122, v243
	v_pk_mul_f32 v[110:111], v[110:111], v[122:123] op_sel_hi:[1,0]
	v_pk_mul_f32 v[108:109], v[108:109], v[122:123] op_sel_hi:[1,0]
	v_pk_mul_f32 v[106:107], v[106:107], v[122:123] op_sel_hi:[1,0]
	v_pk_mul_f32 v[104:105], v[104:105], v[122:123] op_sel_hi:[1,0]
	s_cbranch_vccnz .LBB0_213
	v_mov_b64_e32 v[116:117], v[106:107]
	v_mov_b64_e32 v[120:121], v[110:111]
	s_cmpk_lt_u32 s1, 0xc00
	v_mov_b64_e32 v[114:115], v[104:105]
	v_mov_b64_e32 v[118:119], v[108:109]
	s_cbranch_scc1 .LBB0_212
	v_mul_f32_e32 v113, v104, v104
	v_fmamk_f32 v113, v113, 0x3dd2d3e8, v214
	v_mul_f32_e32 v114, v109, v109
	v_mul_f32_e64 v113, v104, -v113
	v_fmamk_f32 v114, v114, 0x3dd2d3e8, v214
	v_exp_f32_e32 v113, v113
	v_mul_f32_e64 v114, v109, -v114
	v_exp_f32_e32 v115, v114
	v_mul_f32_e32 v117, v106, v106
	v_add_f32_e32 v113, 1.0, v113
	v_mul_f32_e32 v112, v108, v108
	v_rcp_f32_e32 v114, v113
	v_add_f32_e32 v113, 1.0, v115
	v_mul_f32_e32 v115, v105, v105
	v_mul_f32_e32 v116, v110, v110
	v_fmamk_f32 v117, v117, 0x3dd2d3e8, v214
	v_mul_f32_e32 v118, v111, v111
	v_mul_f32_e32 v119, v107, v107
	v_fmamk_f32 v112, v112, 0x3dd2d3e8, v214
	v_fmamk_f32 v115, v115, 0x3dd2d3e8, v214
	v_fmamk_f32 v116, v116, 0x3dd2d3e8, v214
	v_mul_f32_e64 v117, v106, -v117
	v_fmamk_f32 v118, v118, 0x3dd2d3e8, v214
	v_fmamk_f32 v119, v119, 0x3dd2d3e8, v214
	v_mul_f32_e64 v112, v108, -v112
	v_mul_f32_e64 v115, v105, -v115
	v_mul_f32_e64 v116, v110, -v116
	v_exp_f32_e32 v117, v117
	v_mul_f32_e64 v118, v111, -v118
	v_mul_f32_e64 v119, v107, -v119
	v_exp_f32_e32 v112, v112
	v_exp_f32_e32 v115, v115
	v_exp_f32_e32 v116, v116
	v_exp_f32_e32 v118, v118
	v_exp_f32_e32 v119, v119
	v_add_f32_e32 v117, 1.0, v117
	v_add_f32_e32 v112, 1.0, v112
	v_add_f32_e32 v115, 1.0, v115
	v_add_f32_e32 v116, 1.0, v116
	v_rcp_f32_e32 v126, v117
	v_add_f32_e32 v117, 1.0, v118
	v_add_f32_e32 v118, 1.0, v119
	v_rcp_f32_e32 v112, v112
	v_rcp_f32_e32 v113, v113
	v_rcp_f32_e32 v116, v116
	v_rcp_f32_e32 v117, v117
	v_rcp_f32_e32 v127, v118
	v_rcp_f32_e32 v115, v115
	v_pk_mul_f32 v[118:119], v[108:109], v[112:113]
	v_pk_mul_f32 v[120:121], v[110:111], v[116:117]
	v_pk_mul_f32 v[116:117], v[106:107], v[126:127]
	v_pk_mul_f32 v[114:115], v[104:105], v[114:115]

;   __device__ __forceinline__ bf16_t* Z() const { return (bf16_t*)(ws + 456 * MB); }
;   __device__ __forceinline__ float* cosT() const { return (float*)(ws + 904 * MB); }
;   __device__ __forceinline__ float* sinT() const { return (float*)(ws + 905 * MB); }
; template <int MODE>
; __device__ __forceinline__ void gemm_epilogue(const Params& p, int layer, const f32x4 (&acc)[2][2][4][2], int pm, int pn, int wr, int wc, int fr, int fq) {
;     ...
;         const int pos = (row < NPROMPT) ? (row & 8191) : (row & 4095);
; #pragma unroll
;         for (int bj = 0; bj < 2; ++bj) {
;           const int colt = pn * 256 + bj * 128 + wc * 32;
;           f32x4 v0 = acc[ai][bj][m][0] * rsv, v1 = acc[ai][bj][m][1] * rsv;
;           bf16_t* zp = p.Z() + (size_t)row * LDZ + colt;
;           if (colt < 2048) {
;             const int ti = pos * 32 + 16 * (wc & 1) + 4 * fq;
;             const f32x4 c = *(const f32x4*)(p.cosT() + ti), s = *(const f32x4*)(p.sinT() + ti);
;             const float qs = (colt < 1024) ? 0.18033688011112042f : 1.f;
;             const f32x4 o0 = (v0 * c - v1 * s) * qs, o1 = (v1 * c + v0 * s) * qs;
;             const u32x4 w = {cvtpk(o0[0], o0[1]), cvtpk(o0[2], o0[3]), cvtpk(o1[0], o1[1]), cvtpk(o1[2], o1[3])};
;             *(u32x4*)(zp + 8 * fq) = w;
.LBB0_213:
	v_cndmask_b32_e64 v116, v252, v238, s[6:7]
	v_bitop3_b32 v116, v116, v146, 16 bitop3:0xe0
	v_lshl_or_b32 v116, v116, 5, v153
	s_and_b64 vcc, exec, s[8:9]
	v_lshlrev_b32_e32 v118, 2, v116
	s_cbranch_vccz .LBB0_215
	global_load_dwordx4 v[112:115], v118, s[18:19]
	global_load_dwordx4 v[126:129], v118, s[16:17]
	s_cmpk_lt_i32 s46, 0x400
	s_cselect_b64 vcc, -1, 0
	v_cndmask_b32_e32 v116, 1.0, v220, vcc
	s_waitcnt vmcnt(0)
	v_mov_b64_e32 v[216:217], v[112:113]
	v_mov_b64_e32 v[218:219], v[114:115]
	v_mov_b64_e32 v[222:223], v[126:127]
	v_mov_b64_e32 v[224:225], v[128:129]
	v_pk_mul_f32 v[120:121], v[106:107], v[114:115]
	v_pk_mul_f32 v[130:131], v[104:105], v[112:113]
	v_pk_mul_f32 v[114:115], v[110:111], v[114:115]
	v_pk_mul_f32 v[112:113], v[108:109], v[112:113]
	v_pk_fma_f32 v[110:111], v[110:111], v[128:129], v[120:121] neg_lo:[0,0,1] neg_hi:[0,0,1]
	v_pk_fma_f32 v[108:109], v[108:109], v[126:127], v[130:131] neg_lo:[0,0,1] neg_hi:[0,0,1]
	v_pk_fma_f32 v[106:107], v[106:107], v[128:129], v[114:115]
	v_pk_fma_f32 v[104:105], v[104:105], v[126:127], v[112:113]
	v_pk_mul_f32 v[110:111], v[116:117], v[110:111] op_sel_hi:[0,1]
	v_pk_mul_f32 v[108:109], v[116:117], v[108:109] op_sel_hi:[0,1]
	v_pk_mul_f32 v[106:107], v[116:117], v[106:107] op_sel_hi:[0,1]
	v_pk_mul_f32 v[104:105], v[116:117], v[104:105] op_sel_hi:[0,1]
	v_cvt_pk_bf16_f32 v112, v108, v109
	v_cvt_pk_bf16_f32 v113, v110, v111
	v_cvt_pk_bf16_f32 v114, v104, v105
	v_cvt_pk_bf16_f32 v115, v106, v107

;   __device__ __forceinline__ bf16_t* Z() const { return (bf16_t*)(ws + 456 * MB); }
;   __device__ __forceinline__ float* cosT() const { return (float*)(ws + 904 * MB); }
;   __device__ __forceinline__ float* sinT() const { return (float*)(ws + 905 * MB); }
;   __device__ __forceinline__ float* RS() const { return (float*)(ws + 906 * MB); }
; template <int MODE>
; __device__ __forceinline__ void gemm_epilogue(const Params& p, int layer, const f32x4 (&acc)[2][2][4][2], int pm, int pn, int wr, int wc, int fr, int fq) {
;     ...
;       const int row = pm * 256 + ai * 128 + wr * 64 + m * 16 + fr;
;       if (MODE == 0) {
;         const float rsv = p.RS()[row];
;         const int pos = (row < NPROMPT) ? (row & 8191) : (row & 4095);
; #pragma unroll
;         for (int bj = 0; bj < 2; ++bj) {
;           const int colt = pn * 256 + bj * 128 + wc * 32;
;           f32x4 v0 = acc[ai][bj][m][0] * rsv, v1 = acc[ai][bj][m][1] * rsv;
;           bf16_t* zp = p.Z() + (size_t)row * LDZ + colt;
;           if (colt < 2048) {
;             const int ti = pos * 32 + 16 * (wc & 1) + 4 * fq;
;             const f32x4 c = *(const f32x4*)(p.cosT() + ti), s = *(const f32x4*)(p.sinT() + ti);
;             const float qs = (colt < 1024) ? 0.18033688011112042f : 1.f;
;             const f32x4 o0 = (v0 * c - v1 * s) * qs, o1 = (v1 * c + v0 * s) * qs;
;             const u32x4 w = {cvtpk(o0[0], o0[1]), cvtpk(o0[2], o0[3]), cvtpk(o1[0], o1[1]), cvtpk(o1[2], o1[3])};
;             *(u32x4*)(zp + 8 * fq) = w;
;           } else {
;             if (colt >= 3072) {
; #pragma unroll
;               for (int e = 0; e < 4; ++e) { v0[e] = gelu_tanh(v0[e]); v1[e] = gelu_tanh(v1[e]); }
;             }
;             const u32x4 w = {cvtpk(v0[0], v0[1]), cvtpk(v0[2], v0[3]), cvtpk(v1[0], v1[1]), cvtpk(v1[2], v1[3])};
;             *(u32x4*)(zp + 8 * fq) = w;
.LBB0_219:
	s_and_b64 vcc, exec, s[8:9]
	s_cbranch_vccz .LBB0_221
	v_mov_b64_e32 v[104:105], v[216:217]
	v_mov_b64_e32 v[106:107], v[218:219]
	v_mov_b64_e32 v[108:109], v[222:223]
	v_mov_b64_e32 v[110:111], v[224:225]
	s_cmpk_lt_i32 s21, 0x400
	s_cselect_b64 vcc, -1, 0
	v_cndmask_b32_e32 v112, 1.0, v220, vcc
	v_pk_mul_f32 v[114:115], v[98:99], v[106:107]
	v_pk_mul_f32 v[118:119], v[96:97], v[104:105]
	v_pk_mul_f32 v[106:107], v[102:103], v[106:107]
	v_pk_mul_f32 v[104:105], v[100:101], v[104:105]
	v_pk_fma_f32 v[102:103], v[102:103], v[110:111], v[114:115] neg_lo:[0,0,1] neg_hi:[0,0,1]
	v_pk_fma_f32 v[100:101], v[100:101], v[108:109], v[118:119] neg_lo:[0,0,1] neg_hi:[0,0,1]
	v_pk_fma_f32 v[98:99], v[98:99], v[110:111], v[106:107]
	v_pk_fma_f32 v[96:97], v[96:97], v[108:109], v[104:105]
	v_pk_mul_f32 v[102:103], v[112:113], v[102:103] op_sel_hi:[0,1]
	v_pk_mul_f32 v[100:101], v[112:113], v[100:101] op_sel_hi:[0,1]
	v_pk_mul_f32 v[98:99], v[112:113], v[98:99] op_sel_hi:[0,1]
	v_pk_mul_f32 v[96:97], v[112:113], v[96:97] op_sel_hi:[0,1]
	v_cvt_pk_bf16_f32 v104, v100, v101
	v_cvt_pk_bf16_f32 v105, v102, v103
	v_cvt_pk_bf16_f32 v106, v96, v97
	v_cvt_pk_bf16_f32 v107, v98, v99
.LBB0_221:
	v_or_b32_e32 v108, 32, v146
	v_ashrrev_i32_e32 v109, 31, v108
	global_store_dwordx4 v[116:117], v[104:107], off offset:256
	v_lshl_add_u64 v[96:97], v[108:109], 2, s[12:13]
	s_and_b64 vcc, exec, s[4:5]
	v_cmp_gt_i32_e64 s[8:9], s2, v108
	s_mov_b64 s[48:49], -1
	v_mov_b32_e32 v106, v244
	v_pk_mul_f32 v[94:95], v[94:95], v[106:107] op_sel_hi:[1,0]
	v_pk_mul_f32 v[92:93], v[92:93], v[106:107] op_sel_hi:[1,0]
	v_pk_mul_f32 v[90:91], v[90:91], v[106:107] op_sel_hi:[1,0]
	v_pk_mul_f32 v[88:89], v[88:89], v[106:107] op_sel_hi:[1,0]
	s_cbranch_vccnz .LBB0_225
	v_mov_b64_e32 v[100:101], v[90:91]
	v_mov_b64_e32 v[104:105], v[94:95]
	s_cmpk_lt_u32 s1, 0xc00
	v_mov_b64_e32 v[98:99], v[88:89]
	v_mov_b64_e32 v[102:103], v[92:93]
	s_cbranch_scc1 .LBB0_224
	v_mul_f32_e32 v97, v88, v88
	v_fmamk_f32 v97, v97, 0x3dd2d3e8, v214
	v_mul_f32_e32 v98, v93, v93
	v_mul_f32_e64 v97, v88, -v97
	v_fmamk_f32 v98, v98, 0x3dd2d3e8, v214
	v_exp_f32_e32 v97, v97
	v_mul_f32_e64 v98, v93, -v98
	v_exp_f32_e32 v99, v98
	v_mul_f32_e32 v101, v90, v90
	v_add_f32_e32 v97, 1.0, v97
	v_mul_f32_e32 v96, v92, v92
	v_rcp_f32_e32 v98, v97
	v_add_f32_e32 v97, 1.0, v99
	v_mul_f32_e32 v99, v89, v89
	v_mul_f32_e32 v100, v94, v94
	v_fmamk_f32 v101, v101, 0x3dd2d3e8, v214
	v_mul_f32_e32 v102, v95, v95
	v_mul_f32_e32 v103, v91, v91
	v_fmamk_f32 v96, v96, 0x3dd2d3e8, v214
	v_fmamk_f32 v99, v99, 0x3dd2d3e8, v214
	v_fmamk_f32 v100, v100, 0x3dd2d3e8, v214
	v_mul_f32_e64 v101, v90, -v101
	v_fmamk_f32 v102, v102, 0x3dd2d3e8, v214
	v_fmamk_f32 v103, v103, 0x3dd2d3e8, v214
	v_mul_f32_e64 v96, v92, -v96
	v_mul_f32_e64 v99, v89, -v99
	v_mul_f32_e64 v100, v94, -v100
	v_exp_f32_e32 v101, v101
	v_mul_f32_e64 v102, v95, -v102
	v_mul_f32_e64 v103, v91, -v103
	v_exp_f32_e32 v96, v96
	v_exp_f32_e32 v99, v99
	v_exp_f32_e32 v100, v100
	v_exp_f32_e32 v102, v102
	v_exp_f32_e32 v103, v103
	v_add_f32_e32 v101, 1.0, v101
	v_add_f32_e32 v96, 1.0, v96
	v_add_f32_e32 v99, 1.0, v99
	v_add_f32_e32 v100, 1.0, v100
	v_rcp_f32_e32 v110, v101
	v_add_f32_e32 v101, 1.0, v102
	v_add_f32_e32 v102, 1.0, v103
	v_rcp_f32_e32 v96, v96
	v_rcp_f32_e32 v97, v97
	v_rcp_f32_e32 v100, v100
	v_rcp_f32_e32 v101, v101
	v_rcp_f32_e32 v111, v102
	v_rcp_f32_e32 v99, v99
	v_pk_mul_f32 v[102:103], v[92:93], v[96:97]
	v_pk_mul_f32 v[104:105], v[94:95], v[100:101]
	v_pk_mul_f32 v[100:101], v[90:91], v[110:111]
	v_pk_mul_f32 v[98:99], v[88:89], v[98:99]

;   __device__ __forceinline__ bf16_t* Z() const { return (bf16_t*)(ws + 456 * MB); }
;   __device__ __forceinline__ float* cosT() const { return (float*)(ws + 904 * MB); }
;   __device__ __forceinline__ float* sinT() const { return (float*)(ws + 905 * MB); }
; template <int MODE>
; __device__ __forceinline__ void gemm_epilogue(const Params& p, int layer, const f32x4 (&acc)[2][2][4][2], int pm, int pn, int wr, int wc, int fr, int fq) {
;     ...
;         const int pos = (row < NPROMPT) ? (row & 8191) : (row & 4095);
; #pragma unroll
;         for (int bj = 0; bj < 2; ++bj) {
;           const int colt = pn * 256 + bj * 128 + wc * 32;
;           f32x4 v0 = acc[ai][bj][m][0] * rsv, v1 = acc[ai][bj][m][1] * rsv;
;           bf16_t* zp = p.Z() + (size_t)row * LDZ + colt;
;           if (colt < 2048) {
;             const int ti = pos * 32 + 16 * (wc & 1) + 4 * fq;
;             const f32x4 c = *(const f32x4*)(p.cosT() + ti), s = *(const f32x4*)(p.sinT() + ti);
;             const float qs = (colt < 1024) ? 0.18033688011112042f : 1.f;
;             const f32x4 o0 = (v0 * c - v1 * s) * qs, o1 = (v1 * c + v0 * s) * qs;
;             const u32x4 w = {cvtpk(o0[0], o0[1]), cvtpk(o0[2], o0[3]), cvtpk(o1[0], o1[1]), cvtpk(o1[2], o1[3])};
;             *(u32x4*)(zp + 8 * fq) = w;
.LBB0_225:
	v_cndmask_b32_e64 v100, v226, v239, s[8:9]
	v_bitop3_b32 v100, v100, v146, 32 bitop3:0xe0
	v_lshl_or_b32 v100, v100, 5, v153
	s_and_b64 vcc, exec, s[48:49]
	v_lshlrev_b32_e32 v102, 2, v100
	s_cbranch_vccz .LBB0_227
	global_load_dwordx4 v[96:99], v102, s[18:19]
	global_load_dwordx4 v[110:113], v102, s[16:17]
	s_cmpk_lt_i32 s46, 0x400
	s_cselect_b64 vcc, -1, 0
	v_cndmask_b32_e32 v100, 1.0, v220, vcc
	s_waitcnt vmcnt(0)
	v_mov_b64_e32 v[216:217], v[96:97]
	v_mov_b64_e32 v[218:219], v[98:99]
	v_mov_b64_e32 v[222:223], v[110:111]
	v_mov_b64_e32 v[224:225], v[112:113]
	v_pk_mul_f32 v[104:105], v[90:91], v[98:99]
	v_pk_mul_f32 v[114:115], v[88:89], v[96:97]
	v_pk_mul_f32 v[98:99], v[94:95], v[98:99]
	v_pk_mul_f32 v[96:97], v[92:93], v[96:97]
	v_pk_fma_f32 v[94:95], v[94:95], v[112:113], v[104:105] neg_lo:[0,0,1] neg_hi:[0,0,1]
	v_pk_fma_f32 v[92:93], v[92:93], v[110:111], v[114:115] neg_lo:[0,0,1] neg_hi:[0,0,1]
	v_pk_fma_f32 v[90:91], v[90:91], v[112:113], v[98:99]
	v_pk_fma_f32 v[88:89], v[88:89], v[110:111], v[96:97]
	v_pk_mul_f32 v[94:95], v[100:101], v[94:95] op_sel_hi:[0,1]
	v_pk_mul_f32 v[92:93], v[100:101], v[92:93] op_sel_hi:[0,1]
	v_pk_mul_f32 v[90:91], v[100:101], v[90:91] op_sel_hi:[0,1]
	v_pk_mul_f32 v[88:89], v[100:101], v[88:89] op_sel_hi:[0,1]
	v_cvt_pk_bf16_f32 v96, v92, v93
	v_cvt_pk_bf16_f32 v97, v94, v95
	v_cvt_pk_bf16_f32 v98, v88, v89
	v_cvt_pk_bf16_f32 v99, v90, v91

;   __device__ __forceinline__ bf16_t* Z() const { return (bf16_t*)(ws + 456 * MB); }
;   __device__ __forceinline__ float* cosT() const { return (float*)(ws + 904 * MB); }
;   __device__ __forceinline__ float* sinT() const { return (float*)(ws + 905 * MB); }
;   __device__ __forceinline__ float* RS() const { return (float*)(ws + 906 * MB); }
; template <int MODE>
; __device__ __forceinline__ void gemm_epilogue(const Params& p, int layer, const f32x4 (&acc)[2][2][4][2], int pm, int pn, int wr, int wc, int fr, int fq) {
;     ...
;       const int row = pm * 256 + ai * 128 + wr * 64 + m * 16 + fr;
;       if (MODE == 0) {
;         const float rsv = p.RS()[row];
;         const int pos = (row < NPROMPT) ? (row & 8191) : (row & 4095);
; #pragma unroll
;         for (int bj = 0; bj < 2; ++bj) {
;           const int colt = pn * 256 + bj * 128 + wc * 32;
;           f32x4 v0 = acc[ai][bj][m][0] * rsv, v1 = acc[ai][bj][m][1] * rsv;
;           bf16_t* zp = p.Z() + (size_t)row * LDZ + colt;
;           if (colt < 2048) {
;             const int ti = pos * 32 + 16 * (wc & 1) + 4 * fq;
;             const f32x4 c = *(const f32x4*)(p.cosT() + ti), s = *(const f32x4*)(p.sinT() + ti);
;             const float qs = (colt < 1024) ? 0.18033688011112042f : 1.f;
;             const f32x4 o0 = (v0 * c - v1 * s) * qs, o1 = (v1 * c + v0 * s) * qs;
;             const u32x4 w = {cvtpk(o0[0], o0[1]), cvtpk(o0[2], o0[3]), cvtpk(o1[0], o1[1]), cvtpk(o1[2], o1[3])};
;             *(u32x4*)(zp + 8 * fq) = w;
;           } else {
;             if (colt >= 3072) {
; #pragma unroll
;               for (int e = 0; e < 4; ++e) { v0[e] = gelu_tanh(v0[e]); v1[e] = gelu_tanh(v1[e]); }
;             }
;             const u32x4 w = {cvtpk(v0[0], v0[1]), cvtpk(v0[2], v0[3]), cvtpk(v1[0], v1[1]), cvtpk(v1[2], v1[3])};
;             *(u32x4*)(zp + 8 * fq) = w;
.LBB0_231:
	s_and_b64 vcc, exec, s[8:9]
	s_cbranch_vccz .LBB0_233
	v_mov_b64_e32 v[88:89], v[216:217]
	v_mov_b64_e32 v[90:91], v[218:219]
	v_mov_b64_e32 v[92:93], v[222:223]
	v_mov_b64_e32 v[94:95], v[224:225]
	s_cmpk_lt_i32 s21, 0x400
	s_cselect_b64 vcc, -1, 0
	v_cndmask_b32_e32 v96, 1.0, v220, vcc
	v_pk_mul_f32 v[98:99], v[82:83], v[90:91]
	v_pk_mul_f32 v[102:103], v[80:81], v[88:89]
	v_pk_mul_f32 v[90:91], v[86:87], v[90:91]
	v_pk_mul_f32 v[88:89], v[84:85], v[88:89]
	v_pk_fma_f32 v[86:87], v[86:87], v[94:95], v[98:99] neg_lo:[0,0,1] neg_hi:[0,0,1]
	v_pk_fma_f32 v[84:85], v[84:85], v[92:93], v[102:103] neg_lo:[0,0,1] neg_hi:[0,0,1]
	v_pk_fma_f32 v[82:83], v[82:83], v[94:95], v[90:91]
	v_pk_fma_f32 v[80:81], v[80:81], v[92:93], v[88:89]
	v_pk_mul_f32 v[86:87], v[96:97], v[86:87] op_sel_hi:[0,1]
	v_pk_mul_f32 v[84:85], v[96:97], v[84:85] op_sel_hi:[0,1]
	v_pk_mul_f32 v[82:83], v[96:97], v[82:83] op_sel_hi:[0,1]
	v_pk_mul_f32 v[80:81], v[96:97], v[80:81] op_sel_hi:[0,1]
	v_cvt_pk_bf16_f32 v88, v84, v85
	v_cvt_pk_bf16_f32 v89, v86, v87
	v_cvt_pk_bf16_f32 v90, v80, v81
	v_cvt_pk_bf16_f32 v91, v82, v83
.LBB0_233:
	v_or_b32_e32 v92, 48, v146
	v_ashrrev_i32_e32 v93, 31, v92
	global_store_dwordx4 v[100:101], v[88:91], off offset:256
	v_lshl_add_u64 v[80:81], v[92:93], 2, s[12:13]
	s_and_b64 vcc, exec, s[4:5]
	v_cmp_gt_i32_e64 s[8:9], s2, v92
	s_mov_b64 s[48:49], -1
	v_mov_b32_e32 v90, v245
	v_pk_mul_f32 v[78:79], v[78:79], v[90:91] op_sel_hi:[1,0]
	v_pk_mul_f32 v[76:77], v[76:77], v[90:91] op_sel_hi:[1,0]
	v_pk_mul_f32 v[74:75], v[74:75], v[90:91] op_sel_hi:[1,0]
	v_pk_mul_f32 v[72:73], v[72:73], v[90:91] op_sel_hi:[1,0]
	s_cbranch_vccnz .LBB0_237
	v_mov_b64_e32 v[84:85], v[74:75]
	v_mov_b64_e32 v[88:89], v[78:79]
	s_cmpk_lt_u32 s1, 0xc00
	v_mov_b64_e32 v[82:83], v[72:73]
	v_mov_b64_e32 v[86:87], v[76:77]
	s_cbranch_scc1 .LBB0_236
	v_mul_f32_e32 v81, v72, v72
	v_fmamk_f32 v81, v81, 0x3dd2d3e8, v214
	v_mul_f32_e32 v82, v77, v77
	v_mul_f32_e64 v81, v72, -v81
	v_fmamk_f32 v82, v82, 0x3dd2d3e8, v214
	v_exp_f32_e32 v81, v81
	v_mul_f32_e64 v82, v77, -v82
	v_exp_f32_e32 v83, v82
	v_mul_f32_e32 v85, v74, v74
	v_add_f32_e32 v81, 1.0, v81
	v_mul_f32_e32 v80, v76, v76
	v_rcp_f32_e32 v82, v81
	v_add_f32_e32 v81, 1.0, v83
	v_mul_f32_e32 v83, v73, v73
	v_mul_f32_e32 v84, v78, v78
	v_fmamk_f32 v85, v85, 0x3dd2d3e8, v214
	v_mul_f32_e32 v86, v79, v79
	v_mul_f32_e32 v87, v75, v75
	v_fmamk_f32 v80, v80, 0x3dd2d3e8, v214
	v_fmamk_f32 v83, v83, 0x3dd2d3e8, v214
	v_fmamk_f32 v84, v84, 0x3dd2d3e8, v214
	v_mul_f32_e64 v85, v74, -v85
	v_fmamk_f32 v86, v86, 0x3dd2d3e8, v214
	v_fmamk_f32 v87, v87, 0x3dd2d3e8, v214
	v_mul_f32_e64 v80, v76, -v80
	v_mul_f32_e64 v83, v73, -v83
	v_mul_f32_e64 v84, v78, -v84
	v_exp_f32_e32 v85, v85
	v_mul_f32_e64 v86, v79, -v86
	v_mul_f32_e64 v87, v75, -v87
	v_exp_f32_e32 v80, v80
	v_exp_f32_e32 v83, v83
	v_exp_f32_e32 v84, v84
	v_exp_f32_e32 v86, v86
	v_exp_f32_e32 v87, v87
	v_add_f32_e32 v85, 1.0, v85
	v_add_f32_e32 v80, 1.0, v80
	v_add_f32_e32 v83, 1.0, v83
	v_add_f32_e32 v84, 1.0, v84
	v_rcp_f32_e32 v94, v85
	v_add_f32_e32 v85, 1.0, v86
	v_add_f32_e32 v86, 1.0, v87
	v_rcp_f32_e32 v80, v80
	v_rcp_f32_e32 v81, v81
	v_rcp_f32_e32 v84, v84
	v_rcp_f32_e32 v85, v85
	v_rcp_f32_e32 v95, v86
	v_rcp_f32_e32 v83, v83
	v_pk_mul_f32 v[86:87], v[76:77], v[80:81]
	v_pk_mul_f32 v[88:89], v[78:79], v[84:85]
	v_pk_mul_f32 v[84:85], v[74:75], v[94:95]
	v_pk_mul_f32 v[82:83], v[72:73], v[82:83]

;   __device__ __forceinline__ bf16_t* Z() const { return (bf16_t*)(ws + 456 * MB); }
;   __device__ __forceinline__ float* cosT() const { return (float*)(ws + 904 * MB); }
;   __device__ __forceinline__ float* sinT() const { return (float*)(ws + 905 * MB); }
; template <int MODE>
; __device__ __forceinline__ void gemm_epilogue(const Params& p, int layer, const f32x4 (&acc)[2][2][4][2], int pm, int pn, int wr, int wc, int fr, int fq) {
;     ...
;         const int pos = (row < NPROMPT) ? (row & 8191) : (row & 4095);
; #pragma unroll
;         for (int bj = 0; bj < 2; ++bj) {
;           const int colt = pn * 256 + bj * 128 + wc * 32;
;           f32x4 v0 = acc[ai][bj][m][0] * rsv, v1 = acc[ai][bj][m][1] * rsv;
;           bf16_t* zp = p.Z() + (size_t)row * LDZ + colt;
;           if (colt < 2048) {
;             const int ti = pos * 32 + 16 * (wc & 1) + 4 * fq;
;             const f32x4 c = *(const f32x4*)(p.cosT() + ti), s = *(const f32x4*)(p.sinT() + ti);
;             const float qs = (colt < 1024) ? 0.18033688011112042f : 1.f;
;             const f32x4 o0 = (v0 * c - v1 * s) * qs, o1 = (v1 * c + v0 * s) * qs;
;             const u32x4 w = {cvtpk(o0[0], o0[1]), cvtpk(o0[2], o0[3]), cvtpk(o1[0], o1[1]), cvtpk(o1[2], o1[3])};
;             *(u32x4*)(zp + 8 * fq) = w;
.LBB0_237:
	v_cndmask_b32_e64 v84, v240, v241, s[8:9]
	v_bitop3_b32 v84, v84, v146, 48 bitop3:0xe0
	v_lshl_or_b32 v84, v84, 5, v153
	s_and_b64 vcc, exec, s[48:49]
	v_lshlrev_b32_e32 v86, 2, v84
	s_cbranch_vccz .LBB0_239
	global_load_dwordx4 v[80:83], v86, s[18:19]
	global_load_dwordx4 v[94:97], v86, s[16:17]
	s_cmpk_lt_i32 s46, 0x400
	s_cselect_b64 vcc, -1, 0
	v_cndmask_b32_e32 v84, 1.0, v220, vcc
	s_waitcnt vmcnt(0)
	v_mov_b64_e32 v[216:217], v[80:81]
	v_mov_b64_e32 v[218:219], v[82:83]
	v_mov_b64_e32 v[222:223], v[94:95]
	v_mov_b64_e32 v[224:225], v[96:97]
	v_pk_mul_f32 v[88:89], v[74:75], v[82:83]
	v_pk_mul_f32 v[98:99], v[72:73], v[80:81]
	v_pk_mul_f32 v[82:83], v[78:79], v[82:83]
	v_pk_mul_f32 v[80:81], v[76:77], v[80:81]
	v_pk_fma_f32 v[78:79], v[78:79], v[96:97], v[88:89] neg_lo:[0,0,1] neg_hi:[0,0,1]
	v_pk_fma_f32 v[76:77], v[76:77], v[94:95], v[98:99] neg_lo:[0,0,1] neg_hi:[0,0,1]
	v_pk_fma_f32 v[74:75], v[74:75], v[96:97], v[82:83]
	v_pk_fma_f32 v[72:73], v[72:73], v[94:95], v[80:81]
	v_pk_mul_f32 v[78:79], v[84:85], v[78:79] op_sel_hi:[0,1]
	v_pk_mul_f32 v[76:77], v[84:85], v[76:77] op_sel_hi:[0,1]
	v_pk_mul_f32 v[74:75], v[84:85], v[74:75] op_sel_hi:[0,1]
	v_pk_mul_f32 v[72:73], v[84:85], v[72:73] op_sel_hi:[0,1]
	v_cvt_pk_bf16_f32 v80, v76, v77
	v_cvt_pk_bf16_f32 v81, v78, v79
	v_cvt_pk_bf16_f32 v82, v72, v73
	v_cvt_pk_bf16_f32 v83, v74, v75

;   __device__ __forceinline__ bf16_t* Z() const { return (bf16_t*)(ws + 456 * MB); }
;   __device__ __forceinline__ float* cosT() const { return (float*)(ws + 904 * MB); }
;   __device__ __forceinline__ float* sinT() const { return (float*)(ws + 905 * MB); }
;   __device__ __forceinline__ float* RS() const { return (float*)(ws + 906 * MB); }
; template <int MODE>
; __device__ __forceinline__ void gemm_epilogue(const Params& p, int layer, const f32x4 (&acc)[2][2][4][2], int pm, int pn, int wr, int wc, int fr, int fq) {
;     ...
;       const int row = pm * 256 + ai * 128 + wr * 64 + m * 16 + fr;
;       if (MODE == 0) {
;         const float rsv = p.RS()[row];
;         const int pos = (row < NPROMPT) ? (row & 8191) : (row & 4095);
; #pragma unroll
;         for (int bj = 0; bj < 2; ++bj) {
;           const int colt = pn * 256 + bj * 128 + wc * 32;
;           f32x4 v0 = acc[ai][bj][m][0] * rsv, v1 = acc[ai][bj][m][1] * rsv;
;           bf16_t* zp = p.Z() + (size_t)row * LDZ + colt;
;           if (colt < 2048) {
;             const int ti = pos * 32 + 16 * (wc & 1) + 4 * fq;
;             const f32x4 c = *(const f32x4*)(p.cosT() + ti), s = *(const f32x4*)(p.sinT() + ti);
;             const float qs = (colt < 1024) ? 0.18033688011112042f : 1.f;
;             const f32x4 o0 = (v0 * c - v1 * s) * qs, o1 = (v1 * c + v0 * s) * qs;
;             const u32x4 w = {cvtpk(o0[0], o0[1]), cvtpk(o0[2], o0[3]), cvtpk(o1[0], o1[1]), cvtpk(o1[2], o1[3])};
;             *(u32x4*)(zp + 8 * fq) = w;
;           } else {
;             if (colt >= 3072) {
; #pragma unroll
;               for (int e = 0; e < 4; ++e) { v0[e] = gelu_tanh(v0[e]); v1[e] = gelu_tanh(v1[e]); }
;             }
;             const u32x4 w = {cvtpk(v0[0], v0[1]), cvtpk(v0[2], v0[3]), cvtpk(v1[0], v1[1]), cvtpk(v1[2], v1[3])};
;             *(u32x4*)(zp + 8 * fq) = w;
.LBB0_243:
	s_and_b64 vcc, exec, s[8:9]
	s_cbranch_vccz .LBB0_245
	v_mov_b64_e32 v[72:73], v[216:217]
	v_mov_b64_e32 v[74:75], v[218:219]
	v_mov_b64_e32 v[76:77], v[222:223]
	v_mov_b64_e32 v[78:79], v[224:225]
	s_cmpk_lt_i32 s21, 0x400
	s_cselect_b64 vcc, -1, 0
	v_cndmask_b32_e32 v80, 1.0, v220, vcc
	v_pk_mul_f32 v[82:83], v[66:67], v[74:75]
	v_pk_mul_f32 v[86:87], v[64:65], v[72:73]
	v_pk_mul_f32 v[74:75], v[70:71], v[74:75]
	v_pk_mul_f32 v[72:73], v[68:69], v[72:73]
	v_pk_fma_f32 v[70:71], v[70:71], v[78:79], v[82:83] neg_lo:[0,0,1] neg_hi:[0,0,1]
	v_pk_fma_f32 v[68:69], v[68:69], v[76:77], v[86:87] neg_lo:[0,0,1] neg_hi:[0,0,1]
	v_pk_fma_f32 v[66:67], v[66:67], v[78:79], v[74:75]
	v_pk_fma_f32 v[64:65], v[64:65], v[76:77], v[72:73]
	v_pk_mul_f32 v[70:71], v[80:81], v[70:71] op_sel_hi:[0,1]
	v_pk_mul_f32 v[68:69], v[80:81], v[68:69] op_sel_hi:[0,1]
	v_pk_mul_f32 v[66:67], v[80:81], v[66:67] op_sel_hi:[0,1]
	v_pk_mul_f32 v[64:65], v[80:81], v[64:65] op_sel_hi:[0,1]
	v_cvt_pk_bf16_f32 v72, v68, v69
	v_cvt_pk_bf16_f32 v73, v70, v71
	v_cvt_pk_bf16_f32 v74, v64, v65
	v_cvt_pk_bf16_f32 v75, v66, v67
.LBB0_245:
	v_add_u32_e32 v76, 0x80, v146
	v_ashrrev_i32_e32 v77, 31, v76
	global_store_dwordx4 v[84:85], v[72:75], off offset:256
	v_lshl_add_u64 v[64:65], v[76:77], 2, s[12:13]
	s_and_b64 vcc, exec, s[4:5]
	v_cmp_gt_i32_e64 s[8:9], s2, v76
	s_mov_b64 s[48:49], -1
	v_mov_b32_e32 v74, v246
	v_pk_mul_f32 v[62:63], v[62:63], v[74:75] op_sel_hi:[1,0]
	v_pk_mul_f32 v[60:61], v[60:61], v[74:75] op_sel_hi:[1,0]
	v_pk_mul_f32 v[58:59], v[58:59], v[74:75] op_sel_hi:[1,0]
	v_pk_mul_f32 v[56:57], v[56:57], v[74:75] op_sel_hi:[1,0]
	s_cbranch_vccnz .LBB0_249
	v_mov_b64_e32 v[68:69], v[58:59]
	v_mov_b64_e32 v[72:73], v[62:63]
	s_cmpk_lt_u32 s1, 0xc00
	v_mov_b64_e32 v[66:67], v[56:57]
	v_mov_b64_e32 v[70:71], v[60:61]
	s_cbranch_scc1 .LBB0_248
	v_mul_f32_e32 v65, v56, v56
	v_fmamk_f32 v65, v65, 0x3dd2d3e8, v214
	v_mul_f32_e32 v66, v61, v61
	v_mul_f32_e64 v65, v56, -v65
	v_fmamk_f32 v66, v66, 0x3dd2d3e8, v214
	v_exp_f32_e32 v65, v65
	v_mul_f32_e64 v66, v61, -v66
	v_exp_f32_e32 v67, v66
	v_mul_f32_e32 v69, v58, v58
	v_add_f32_e32 v65, 1.0, v65
	v_mul_f32_e32 v64, v60, v60
	v_rcp_f32_e32 v66, v65
	v_add_f32_e32 v65, 1.0, v67
	v_mul_f32_e32 v67, v57, v57
	v_mul_f32_e32 v68, v62, v62
	v_fmamk_f32 v69, v69, 0x3dd2d3e8, v214
	v_mul_f32_e32 v70, v63, v63
	v_mul_f32_e32 v71, v59, v59
	v_fmamk_f32 v64, v64, 0x3dd2d3e8, v214
	v_fmamk_f32 v67, v67, 0x3dd2d3e8, v214
	v_fmamk_f32 v68, v68, 0x3dd2d3e8, v214
	v_mul_f32_e64 v69, v58, -v69
	v_fmamk_f32 v70, v70, 0x3dd2d3e8, v214
	v_fmamk_f32 v71, v71, 0x3dd2d3e8, v214
	v_mul_f32_e64 v64, v60, -v64
	v_mul_f32_e64 v67, v57, -v67
	v_mul_f32_e64 v68, v62, -v68
	v_exp_f32_e32 v69, v69
	v_mul_f32_e64 v70, v63, -v70
	v_mul_f32_e64 v71, v59, -v71
	v_exp_f32_e32 v64, v64
	v_exp_f32_e32 v67, v67
	v_exp_f32_e32 v68, v68
	v_exp_f32_e32 v70, v70
	v_exp_f32_e32 v71, v71
	v_add_f32_e32 v69, 1.0, v69
	v_add_f32_e32 v64, 1.0, v64
	v_add_f32_e32 v67, 1.0, v67
	v_add_f32_e32 v68, 1.0, v68
	v_rcp_f32_e32 v78, v69
	v_add_f32_e32 v69, 1.0, v70
	v_add_f32_e32 v70, 1.0, v71
	v_rcp_f32_e32 v64, v64
	v_rcp_f32_e32 v65, v65
	v_rcp_f32_e32 v68, v68
	v_rcp_f32_e32 v69, v69
	v_rcp_f32_e32 v79, v70
	v_rcp_f32_e32 v67, v67
	v_pk_mul_f32 v[70:71], v[60:61], v[64:65]
	v_pk_mul_f32 v[72:73], v[62:63], v[68:69]
	v_pk_mul_f32 v[68:69], v[58:59], v[78:79]
	v_pk_mul_f32 v[66:67], v[56:57], v[66:67]

;   __device__ __forceinline__ bf16_t* Z() const { return (bf16_t*)(ws + 456 * MB); }
;   __device__ __forceinline__ float* cosT() const { return (float*)(ws + 904 * MB); }
;   __device__ __forceinline__ float* sinT() const { return (float*)(ws + 905 * MB); }
; template <int MODE>
; __device__ __forceinline__ void gemm_epilogue(const Params& p, int layer, const f32x4 (&acc)[2][2][4][2], int pm, int pn, int wr, int wc, int fr, int fq) {
;     ...
;         const int pos = (row < NPROMPT) ? (row & 8191) : (row & 4095);
; #pragma unroll
;         for (int bj = 0; bj < 2; ++bj) {
;           const int colt = pn * 256 + bj * 128 + wc * 32;
;           f32x4 v0 = acc[ai][bj][m][0] * rsv, v1 = acc[ai][bj][m][1] * rsv;
;           bf16_t* zp = p.Z() + (size_t)row * LDZ + colt;
;           if (colt < 2048) {
;             const int ti = pos * 32 + 16 * (wc & 1) + 4 * fq;
;             const f32x4 c = *(const f32x4*)(p.cosT() + ti), s = *(const f32x4*)(p.sinT() + ti);
;             const float qs = (colt < 1024) ? 0.18033688011112042f : 1.f;
;             const f32x4 o0 = (v0 * c - v1 * s) * qs, o1 = (v1 * c + v0 * s) * qs;
;             const u32x4 w = {cvtpk(o0[0], o0[1]), cvtpk(o0[2], o0[3]), cvtpk(o1[0], o1[1]), cvtpk(o1[2], o1[3])};
;             *(u32x4*)(zp + 8 * fq) = w;
.LBB0_249:
	v_cndmask_b32_e64 v68, v253, v237, s[8:9]
	v_and_b32_e32 v68, v68, v76
	v_lshl_or_b32 v68, v68, 5, v153
	s_and_b64 vcc, exec, s[48:49]
	v_lshlrev_b32_e32 v70, 2, v68
	s_cbranch_vccz .LBB0_251
	global_load_dwordx4 v[64:67], v70, s[18:19]
	global_load_dwordx4 v[78:81], v70, s[16:17]
	s_cmpk_lt_i32 s46, 0x400
	s_cselect_b64 vcc, -1, 0
	v_cndmask_b32_e32 v68, 1.0, v220, vcc
	s_waitcnt vmcnt(0)
	v_mov_b64_e32 v[216:217], v[64:65]
	v_mov_b64_e32 v[218:219], v[66:67]
	v_mov_b64_e32 v[222:223], v[78:79]
	v_mov_b64_e32 v[224:225], v[80:81]
	v_pk_mul_f32 v[72:73], v[58:59], v[66:67]
	v_pk_mul_f32 v[82:83], v[56:57], v[64:65]
	v_pk_mul_f32 v[66:67], v[62:63], v[66:67]
	v_pk_mul_f32 v[64:65], v[60:61], v[64:65]
	v_pk_fma_f32 v[62:63], v[62:63], v[80:81], v[72:73] neg_lo:[0,0,1] neg_hi:[0,0,1]
	v_pk_fma_f32 v[60:61], v[60:61], v[78:79], v[82:83] neg_lo:[0,0,1] neg_hi:[0,0,1]
	v_pk_fma_f32 v[58:59], v[58:59], v[80:81], v[66:67]
	v_pk_fma_f32 v[56:57], v[56:57], v[78:79], v[64:65]
	v_pk_mul_f32 v[62:63], v[68:69], v[62:63] op_sel_hi:[0,1]
	v_pk_mul_f32 v[60:61], v[68:69], v[60:61] op_sel_hi:[0,1]
	v_pk_mul_f32 v[58:59], v[68:69], v[58:59] op_sel_hi:[0,1]
	v_pk_mul_f32 v[56:57], v[68:69], v[56:57] op_sel_hi:[0,1]
	v_cvt_pk_bf16_f32 v64, v60, v61
	v_cvt_pk_bf16_f32 v65, v62, v63
	v_cvt_pk_bf16_f32 v66, v56, v57
	v_cvt_pk_bf16_f32 v67, v58, v59

;   __device__ __forceinline__ bf16_t* Z() const { return (bf16_t*)(ws + 456 * MB); }
;   __device__ __forceinline__ float* cosT() const { return (float*)(ws + 904 * MB); }
;   __device__ __forceinline__ float* sinT() const { return (float*)(ws + 905 * MB); }
;   __device__ __forceinline__ float* RS() const { return (float*)(ws + 906 * MB); }
; template <int MODE>
; __device__ __forceinline__ void gemm_epilogue(const Params& p, int layer, const f32x4 (&acc)[2][2][4][2], int pm, int pn, int wr, int wc, int fr, int fq) {
;     ...
;       const int row = pm * 256 + ai * 128 + wr * 64 + m * 16 + fr;
;       if (MODE == 0) {
;         const float rsv = p.RS()[row];
;         const int pos = (row < NPROMPT) ? (row & 8191) : (row & 4095);
; #pragma unroll
;         for (int bj = 0; bj < 2; ++bj) {
;           const int colt = pn * 256 + bj * 128 + wc * 32;
;           f32x4 v0 = acc[ai][bj][m][0] * rsv, v1 = acc[ai][bj][m][1] * rsv;
;           bf16_t* zp = p.Z() + (size_t)row * LDZ + colt;
;           if (colt < 2048) {
;             const int ti = pos * 32 + 16 * (wc & 1) + 4 * fq;
;             const f32x4 c = *(const f32x4*)(p.cosT() + ti), s = *(const f32x4*)(p.sinT() + ti);
;             const float qs = (colt < 1024) ? 0.18033688011112042f : 1.f;
;             const f32x4 o0 = (v0 * c - v1 * s) * qs, o1 = (v1 * c + v0 * s) * qs;
;             const u32x4 w = {cvtpk(o0[0], o0[1]), cvtpk(o0[2], o0[3]), cvtpk(o1[0], o1[1]), cvtpk(o1[2], o1[3])};
;             *(u32x4*)(zp + 8 * fq) = w;
;           } else {
;             if (colt >= 3072) {
; #pragma unroll
;               for (int e = 0; e < 4; ++e) { v0[e] = gelu_tanh(v0[e]); v1[e] = gelu_tanh(v1[e]); }
;             }
;             const u32x4 w = {cvtpk(v0[0], v0[1]), cvtpk(v0[2], v0[3]), cvtpk(v1[0], v1[1]), cvtpk(v1[2], v1[3])};
;             *(u32x4*)(zp + 8 * fq) = w;
.LBB0_255:
	s_and_b64 vcc, exec, s[8:9]
	s_cbranch_vccz .LBB0_257
	v_mov_b64_e32 v[56:57], v[216:217]
	v_mov_b64_e32 v[58:59], v[218:219]
	v_mov_b64_e32 v[60:61], v[222:223]
	v_mov_b64_e32 v[62:63], v[224:225]
	s_cmpk_lt_i32 s21, 0x400
	s_cselect_b64 vcc, -1, 0
	v_cndmask_b32_e32 v64, 1.0, v220, vcc
	v_pk_mul_f32 v[66:67], v[50:51], v[58:59]
	v_pk_mul_f32 v[70:71], v[48:49], v[56:57]
	v_pk_mul_f32 v[58:59], v[54:55], v[58:59]
	v_pk_mul_f32 v[56:57], v[52:53], v[56:57]
	v_pk_fma_f32 v[54:55], v[54:55], v[62:63], v[66:67] neg_lo:[0,0,1] neg_hi:[0,0,1]
	v_pk_fma_f32 v[52:53], v[52:53], v[60:61], v[70:71] neg_lo:[0,0,1] neg_hi:[0,0,1]
	v_pk_fma_f32 v[50:51], v[50:51], v[62:63], v[58:59]
	v_pk_fma_f32 v[48:49], v[48:49], v[60:61], v[56:57]
	v_pk_mul_f32 v[54:55], v[64:65], v[54:55] op_sel_hi:[0,1]
	v_pk_mul_f32 v[52:53], v[64:65], v[52:53] op_sel_hi:[0,1]
	v_pk_mul_f32 v[50:51], v[64:65], v[50:51] op_sel_hi:[0,1]
	v_pk_mul_f32 v[48:49], v[64:65], v[48:49] op_sel_hi:[0,1]
	v_cvt_pk_bf16_f32 v56, v52, v53
	v_cvt_pk_bf16_f32 v57, v54, v55
	v_cvt_pk_bf16_f32 v58, v48, v49
	v_cvt_pk_bf16_f32 v59, v50, v51
.LBB0_257:
	v_add_u32_e32 v60, 0x90, v146
	v_ashrrev_i32_e32 v61, 31, v60
	global_store_dwordx4 v[68:69], v[56:59], off offset:256
	v_lshl_add_u64 v[48:49], v[60:61], 2, s[12:13]
	s_and_b64 vcc, exec, s[4:5]
	v_cmp_gt_i32_e64 s[8:9], s2, v60
	s_mov_b64 s[48:49], -1
	v_mov_b32_e32 v58, v247
	v_pk_mul_f32 v[46:47], v[46:47], v[58:59] op_sel_hi:[1,0]
	v_pk_mul_f32 v[44:45], v[44:45], v[58:59] op_sel_hi:[1,0]
	v_pk_mul_f32 v[42:43], v[42:43], v[58:59] op_sel_hi:[1,0]
	v_pk_mul_f32 v[40:41], v[40:41], v[58:59] op_sel_hi:[1,0]
	s_cbranch_vccnz .LBB0_261
	v_mov_b64_e32 v[52:53], v[42:43]
	v_mov_b64_e32 v[56:57], v[46:47]
	s_cmpk_lt_u32 s1, 0xc00
	v_mov_b64_e32 v[50:51], v[40:41]
	v_mov_b64_e32 v[54:55], v[44:45]
	s_cbranch_scc1 .LBB0_260
	v_mul_f32_e32 v49, v40, v40
	v_fmamk_f32 v49, v49, 0x3dd2d3e8, v214
	v_mul_f32_e32 v50, v45, v45
	v_mul_f32_e64 v49, v40, -v49
	v_fmamk_f32 v50, v50, 0x3dd2d3e8, v214
	v_exp_f32_e32 v49, v49
	v_mul_f32_e64 v50, v45, -v50
	v_exp_f32_e32 v51, v50
	v_mul_f32_e32 v53, v42, v42
	v_add_f32_e32 v49, 1.0, v49
	v_mul_f32_e32 v48, v44, v44
	v_rcp_f32_e32 v50, v49
	v_add_f32_e32 v49, 1.0, v51
	v_mul_f32_e32 v51, v41, v41
	v_mul_f32_e32 v52, v46, v46
	v_fmamk_f32 v53, v53, 0x3dd2d3e8, v214
	v_mul_f32_e32 v54, v47, v47
	v_mul_f32_e32 v55, v43, v43
	v_fmamk_f32 v48, v48, 0x3dd2d3e8, v214
	v_fmamk_f32 v51, v51, 0x3dd2d3e8, v214
	v_fmamk_f32 v52, v52, 0x3dd2d3e8, v214
	v_mul_f32_e64 v53, v42, -v53
	v_fmamk_f32 v54, v54, 0x3dd2d3e8, v214
	v_fmamk_f32 v55, v55, 0x3dd2d3e8, v214
	v_mul_f32_e64 v48, v44, -v48
	v_mul_f32_e64 v51, v41, -v51
	v_mul_f32_e64 v52, v46, -v52
	v_exp_f32_e32 v53, v53
	v_mul_f32_e64 v54, v47, -v54
	v_mul_f32_e64 v55, v43, -v55
	v_exp_f32_e32 v48, v48
	v_exp_f32_e32 v51, v51
	v_exp_f32_e32 v52, v52
	v_exp_f32_e32 v54, v54
	v_exp_f32_e32 v55, v55
	v_add_f32_e32 v53, 1.0, v53
	v_add_f32_e32 v48, 1.0, v48
	v_add_f32_e32 v51, 1.0, v51
	v_add_f32_e32 v52, 1.0, v52
	v_rcp_f32_e32 v62, v53
	v_add_f32_e32 v53, 1.0, v54
	v_add_f32_e32 v54, 1.0, v55
	v_rcp_f32_e32 v48, v48
	v_rcp_f32_e32 v49, v49
	v_rcp_f32_e32 v52, v52
	v_rcp_f32_e32 v53, v53
	v_rcp_f32_e32 v63, v54
	v_rcp_f32_e32 v51, v51
	v_pk_mul_f32 v[54:55], v[44:45], v[48:49]
	v_pk_mul_f32 v[56:57], v[46:47], v[52:53]
	v_pk_mul_f32 v[52:53], v[42:43], v[62:63]
	v_pk_mul_f32 v[50:51], v[40:41], v[50:51]

;   __device__ __forceinline__ bf16_t* Z() const { return (bf16_t*)(ws + 456 * MB); }
;   __device__ __forceinline__ float* cosT() const { return (float*)(ws + 904 * MB); }
;   __device__ __forceinline__ float* sinT() const { return (float*)(ws + 905 * MB); }
; template <int MODE>
; __device__ __forceinline__ void gemm_epilogue(const Params& p, int layer, const f32x4 (&acc)[2][2][4][2], int pm, int pn, int wr, int wc, int fr, int fq) {
;     ...
;         const int pos = (row < NPROMPT) ? (row & 8191) : (row & 4095);
; #pragma unroll
;         for (int bj = 0; bj < 2; ++bj) {
;           const int colt = pn * 256 + bj * 128 + wc * 32;
;           f32x4 v0 = acc[ai][bj][m][0] * rsv, v1 = acc[ai][bj][m][1] * rsv;
;           bf16_t* zp = p.Z() + (size_t)row * LDZ + colt;
;           if (colt < 2048) {
;             const int ti = pos * 32 + 16 * (wc & 1) + 4 * fq;
;             const f32x4 c = *(const f32x4*)(p.cosT() + ti), s = *(const f32x4*)(p.sinT() + ti);
;             const float qs = (colt < 1024) ? 0.18033688011112042f : 1.f;
;             const f32x4 o0 = (v0 * c - v1 * s) * qs, o1 = (v1 * c + v0 * s) * qs;
;             const u32x4 w = {cvtpk(o0[0], o0[1]), cvtpk(o0[2], o0[3]), cvtpk(o1[0], o1[1]), cvtpk(o1[2], o1[3])};
;             *(u32x4*)(zp + 8 * fq) = w;
.LBB0_261:
	v_cndmask_b32_e64 v52, v252, v238, s[8:9]
	v_and_b32_e32 v52, v52, v60
	v_lshl_or_b32 v52, v52, 5, v153
	s_and_b64 vcc, exec, s[48:49]
	v_lshlrev_b32_e32 v54, 2, v52
	s_cbranch_vccz .LBB0_263
	global_load_dwordx4 v[48:51], v54, s[18:19]
	global_load_dwordx4 v[62:65], v54, s[16:17]
	s_cmpk_lt_i32 s46, 0x400
	s_cselect_b64 vcc, -1, 0
	v_cndmask_b32_e32 v52, 1.0, v220, vcc
	s_waitcnt vmcnt(0)
	v_mov_b64_e32 v[216:217], v[48:49]
	v_mov_b64_e32 v[218:219], v[50:51]
	v_mov_b64_e32 v[222:223], v[62:63]
	v_mov_b64_e32 v[224:225], v[64:65]
	v_pk_mul_f32 v[56:57], v[42:43], v[50:51]
	v_pk_mul_f32 v[66:67], v[40:41], v[48:49]
	v_pk_mul_f32 v[50:51], v[46:47], v[50:51]
	v_pk_mul_f32 v[48:49], v[44:45], v[48:49]
	v_pk_fma_f32 v[46:47], v[46:47], v[64:65], v[56:57] neg_lo:[0,0,1] neg_hi:[0,0,1]
	v_pk_fma_f32 v[44:45], v[44:45], v[62:63], v[66:67] neg_lo:[0,0,1] neg_hi:[0,0,1]
	v_pk_fma_f32 v[42:43], v[42:43], v[64:65], v[50:51]
	v_pk_fma_f32 v[40:41], v[40:41], v[62:63], v[48:49]
	v_pk_mul_f32 v[46:47], v[52:53], v[46:47] op_sel_hi:[0,1]
	v_pk_mul_f32 v[44:45], v[52:53], v[44:45] op_sel_hi:[0,1]
	v_pk_mul_f32 v[42:43], v[52:53], v[42:43] op_sel_hi:[0,1]
	v_pk_mul_f32 v[40:41], v[52:53], v[40:41] op_sel_hi:[0,1]
	v_cvt_pk_bf16_f32 v48, v44, v45
	v_cvt_pk_bf16_f32 v49, v46, v47
	v_cvt_pk_bf16_f32 v50, v40, v41
	v_cvt_pk_bf16_f32 v51, v42, v43

;   __device__ __forceinline__ bf16_t* Z() const { return (bf16_t*)(ws + 456 * MB); }
;   __device__ __forceinline__ float* cosT() const { return (float*)(ws + 904 * MB); }
;   __device__ __forceinline__ float* sinT() const { return (float*)(ws + 905 * MB); }
;   __device__ __forceinline__ float* RS() const { return (float*)(ws + 906 * MB); }
; template <int MODE>
; __device__ __forceinline__ void gemm_epilogue(const Params& p, int layer, const f32x4 (&acc)[2][2][4][2], int pm, int pn, int wr, int wc, int fr, int fq) {
;     ...
;       const int row = pm * 256 + ai * 128 + wr * 64 + m * 16 + fr;
;       if (MODE == 0) {
;         const float rsv = p.RS()[row];
;         const int pos = (row < NPROMPT) ? (row & 8191) : (row & 4095);
; #pragma unroll
;         for (int bj = 0; bj < 2; ++bj) {
;           const int colt = pn * 256 + bj * 128 + wc * 32;
;           f32x4 v0 = acc[ai][bj][m][0] * rsv, v1 = acc[ai][bj][m][1] * rsv;
;           bf16_t* zp = p.Z() + (size_t)row * LDZ + colt;
;           if (colt < 2048) {
;             const int ti = pos * 32 + 16 * (wc & 1) + 4 * fq;
;             const f32x4 c = *(const f32x4*)(p.cosT() + ti), s = *(const f32x4*)(p.sinT() + ti);
;             const float qs = (colt < 1024) ? 0.18033688011112042f : 1.f;
;             const f32x4 o0 = (v0 * c - v1 * s) * qs, o1 = (v1 * c + v0 * s) * qs;
;             const u32x4 w = {cvtpk(o0[0], o0[1]), cvtpk(o0[2], o0[3]), cvtpk(o1[0], o1[1]), cvtpk(o1[2], o1[3])};
;             *(u32x4*)(zp + 8 * fq) = w;
;           } else {
;             if (colt >= 3072) {
; #pragma unroll
;               for (int e = 0; e < 4; ++e) { v0[e] = gelu_tanh(v0[e]); v1[e] = gelu_tanh(v1[e]); }
;             }
;             const u32x4 w = {cvtpk(v0[0], v0[1]), cvtpk(v0[2], v0[3]), cvtpk(v1[0], v1[1]), cvtpk(v1[2], v1[3])};
;             *(u32x4*)(zp + 8 * fq) = w;
.LBB0_267:
	s_and_b64 vcc, exec, s[8:9]
	s_cbranch_vccz .LBB0_269
	v_mov_b64_e32 v[40:41], v[216:217]
	v_mov_b64_e32 v[42:43], v[218:219]
	v_mov_b64_e32 v[44:45], v[222:223]
	v_mov_b64_e32 v[46:47], v[224:225]
	s_cmpk_lt_i32 s21, 0x400
	s_cselect_b64 vcc, -1, 0
	v_cndmask_b32_e32 v48, 1.0, v220, vcc
	v_pk_mul_f32 v[50:51], v[34:35], v[42:43]
	v_pk_mul_f32 v[54:55], v[32:33], v[40:41]
	v_pk_mul_f32 v[42:43], v[38:39], v[42:43]
	v_pk_mul_f32 v[40:41], v[36:37], v[40:41]
	v_pk_fma_f32 v[38:39], v[38:39], v[46:47], v[50:51] neg_lo:[0,0,1] neg_hi:[0,0,1]
	v_pk_fma_f32 v[36:37], v[36:37], v[44:45], v[54:55] neg_lo:[0,0,1] neg_hi:[0,0,1]
	v_pk_fma_f32 v[34:35], v[34:35], v[46:47], v[42:43]
	v_pk_fma_f32 v[32:33], v[32:33], v[44:45], v[40:41]
	v_pk_mul_f32 v[38:39], v[48:49], v[38:39] op_sel_hi:[0,1]
	v_pk_mul_f32 v[36:37], v[48:49], v[36:37] op_sel_hi:[0,1]
	v_pk_mul_f32 v[34:35], v[48:49], v[34:35] op_sel_hi:[0,1]
	v_pk_mul_f32 v[32:33], v[48:49], v[32:33] op_sel_hi:[0,1]
	v_cvt_pk_bf16_f32 v40, v36, v37
	v_cvt_pk_bf16_f32 v41, v38, v39
	v_cvt_pk_bf16_f32 v42, v32, v33
	v_cvt_pk_bf16_f32 v43, v34, v35
.LBB0_269:
	v_add_u32_e32 v44, 0xa0, v146
	v_ashrrev_i32_e32 v45, 31, v44
	global_store_dwordx4 v[52:53], v[40:43], off offset:256
	v_lshl_add_u64 v[32:33], v[44:45], 2, s[12:13]
	s_and_b64 vcc, exec, s[4:5]
	v_cmp_gt_i32_e64 s[8:9], s2, v44
	s_mov_b64 s[48:49], -1
	v_mov_b32_e32 v42, v248
	v_pk_mul_f32 v[30:31], v[30:31], v[42:43] op_sel_hi:[1,0]
	v_pk_mul_f32 v[28:29], v[28:29], v[42:43] op_sel_hi:[1,0]
	v_pk_mul_f32 v[26:27], v[26:27], v[42:43] op_sel_hi:[1,0]
	v_pk_mul_f32 v[24:25], v[24:25], v[42:43] op_sel_hi:[1,0]
	s_cbranch_vccnz .LBB0_273
	v_mov_b64_e32 v[36:37], v[26:27]
	v_mov_b64_e32 v[40:41], v[30:31]
	s_cmpk_lt_u32 s1, 0xc00
	v_mov_b64_e32 v[34:35], v[24:25]
	v_mov_b64_e32 v[38:39], v[28:29]
	s_cbranch_scc1 .LBB0_272
	v_mul_f32_e32 v33, v24, v24
	v_fmamk_f32 v33, v33, 0x3dd2d3e8, v214
	v_mul_f32_e32 v34, v29, v29
	v_mul_f32_e64 v33, v24, -v33
	v_fmamk_f32 v34, v34, 0x3dd2d3e8, v214
	v_exp_f32_e32 v33, v33
	v_mul_f32_e64 v34, v29, -v34
	v_exp_f32_e32 v35, v34
	v_mul_f32_e32 v37, v26, v26
	v_add_f32_e32 v33, 1.0, v33
	v_mul_f32_e32 v32, v28, v28
	v_rcp_f32_e32 v34, v33
	v_add_f32_e32 v33, 1.0, v35
	v_mul_f32_e32 v35, v25, v25
	v_mul_f32_e32 v36, v30, v30
	v_fmamk_f32 v37, v37, 0x3dd2d3e8, v214
	v_mul_f32_e32 v38, v31, v31
	v_mul_f32_e32 v39, v27, v27
	v_fmamk_f32 v32, v32, 0x3dd2d3e8, v214
	v_fmamk_f32 v35, v35, 0x3dd2d3e8, v214
	v_fmamk_f32 v36, v36, 0x3dd2d3e8, v214
	v_mul_f32_e64 v37, v26, -v37
	v_fmamk_f32 v38, v38, 0x3dd2d3e8, v214
	v_fmamk_f32 v39, v39, 0x3dd2d3e8, v214
	v_mul_f32_e64 v32, v28, -v32
	v_mul_f32_e64 v35, v25, -v35
	v_mul_f32_e64 v36, v30, -v36
	v_exp_f32_e32 v37, v37
	v_mul_f32_e64 v38, v31, -v38
	v_mul_f32_e64 v39, v27, -v39
	v_exp_f32_e32 v32, v32
	v_exp_f32_e32 v35, v35
	v_exp_f32_e32 v36, v36
	v_exp_f32_e32 v38, v38
	v_exp_f32_e32 v39, v39
	v_add_f32_e32 v37, 1.0, v37
	v_add_f32_e32 v32, 1.0, v32
	v_add_f32_e32 v35, 1.0, v35
	v_add_f32_e32 v36, 1.0, v36
	v_rcp_f32_e32 v46, v37
	v_add_f32_e32 v37, 1.0, v38
	v_add_f32_e32 v38, 1.0, v39
	v_rcp_f32_e32 v32, v32
	v_rcp_f32_e32 v33, v33
	v_rcp_f32_e32 v36, v36
	v_rcp_f32_e32 v37, v37
	v_rcp_f32_e32 v47, v38
	v_rcp_f32_e32 v35, v35
	v_pk_mul_f32 v[38:39], v[28:29], v[32:33]
	v_pk_mul_f32 v[40:41], v[30:31], v[36:37]
	v_pk_mul_f32 v[36:37], v[26:27], v[46:47]
	v_pk_mul_f32 v[34:35], v[24:25], v[34:35]

;   __device__ __forceinline__ bf16_t* Z() const { return (bf16_t*)(ws + 456 * MB); }
;   __device__ __forceinline__ float* cosT() const { return (float*)(ws + 904 * MB); }
;   __device__ __forceinline__ float* sinT() const { return (float*)(ws + 905 * MB); }
; template <int MODE>
; __device__ __forceinline__ void gemm_epilogue(const Params& p, int layer, const f32x4 (&acc)[2][2][4][2], int pm, int pn, int wr, int wc, int fr, int fq) {
;     ...
;         const int pos = (row < NPROMPT) ? (row & 8191) : (row & 4095);
; #pragma unroll
;         for (int bj = 0; bj < 2; ++bj) {
;           const int colt = pn * 256 + bj * 128 + wc * 32;
;           f32x4 v0 = acc[ai][bj][m][0] * rsv, v1 = acc[ai][bj][m][1] * rsv;
;           bf16_t* zp = p.Z() + (size_t)row * LDZ + colt;
;           if (colt < 2048) {
;             const int ti = pos * 32 + 16 * (wc & 1) + 4 * fq;
;             const f32x4 c = *(const f32x4*)(p.cosT() + ti), s = *(const f32x4*)(p.sinT() + ti);
;             const float qs = (colt < 1024) ? 0.18033688011112042f : 1.f;
;             const f32x4 o0 = (v0 * c - v1 * s) * qs, o1 = (v1 * c + v0 * s) * qs;
;             const u32x4 w = {cvtpk(o0[0], o0[1]), cvtpk(o0[2], o0[3]), cvtpk(o1[0], o1[1]), cvtpk(o1[2], o1[3])};
;             *(u32x4*)(zp + 8 * fq) = w;
.LBB0_273:
	v_cndmask_b32_e64 v36, v226, v239, s[8:9]
	v_and_b32_e32 v36, v36, v44
	v_lshl_or_b32 v36, v36, 5, v153
	s_and_b64 vcc, exec, s[48:49]
	v_lshlrev_b32_e32 v38, 2, v36
	s_cbranch_vccz .LBB0_275
	global_load_dwordx4 v[32:35], v38, s[18:19]
	global_load_dwordx4 v[46:49], v38, s[16:17]
	s_cmpk_lt_i32 s46, 0x400
	s_cselect_b64 vcc, -1, 0
	v_cndmask_b32_e32 v36, 1.0, v220, vcc
	s_waitcnt vmcnt(0)
	v_mov_b64_e32 v[216:217], v[32:33]
	v_mov_b64_e32 v[218:219], v[34:35]
	v_mov_b64_e32 v[222:223], v[46:47]
	v_mov_b64_e32 v[224:225], v[48:49]
	v_pk_mul_f32 v[40:41], v[26:27], v[34:35]
	v_pk_mul_f32 v[50:51], v[24:25], v[32:33]
	v_pk_mul_f32 v[34:35], v[30:31], v[34:35]
	v_pk_mul_f32 v[32:33], v[28:29], v[32:33]
	v_pk_fma_f32 v[30:31], v[30:31], v[48:49], v[40:41] neg_lo:[0,0,1] neg_hi:[0,0,1]
	v_pk_fma_f32 v[28:29], v[28:29], v[46:47], v[50:51] neg_lo:[0,0,1] neg_hi:[0,0,1]
	v_pk_fma_f32 v[26:27], v[26:27], v[48:49], v[34:35]
	v_pk_fma_f32 v[24:25], v[24:25], v[46:47], v[32:33]
	v_pk_mul_f32 v[30:31], v[36:37], v[30:31] op_sel_hi:[0,1]
	v_pk_mul_f32 v[28:29], v[36:37], v[28:29] op_sel_hi:[0,1]
	v_pk_mul_f32 v[26:27], v[36:37], v[26:27] op_sel_hi:[0,1]
	v_pk_mul_f32 v[24:25], v[36:37], v[24:25] op_sel_hi:[0,1]
	v_cvt_pk_bf16_f32 v32, v28, v29
	v_cvt_pk_bf16_f32 v33, v30, v31
	v_cvt_pk_bf16_f32 v34, v24, v25
	v_cvt_pk_bf16_f32 v35, v26, v27

;   __device__ __forceinline__ bf16_t* Z() const { return (bf16_t*)(ws + 456 * MB); }
;   __device__ __forceinline__ float* cosT() const { return (float*)(ws + 904 * MB); }
;   __device__ __forceinline__ float* sinT() const { return (float*)(ws + 905 * MB); }
;   __device__ __forceinline__ float* RS() const { return (float*)(ws + 906 * MB); }
; template <int MODE>
; __device__ __forceinline__ void gemm_epilogue(const Params& p, int layer, const f32x4 (&acc)[2][2][4][2], int pm, int pn, int wr, int wc, int fr, int fq) {
;     ...
;       const int row = pm * 256 + ai * 128 + wr * 64 + m * 16 + fr;
;       if (MODE == 0) {
;         const float rsv = p.RS()[row];
;         const int pos = (row < NPROMPT) ? (row & 8191) : (row & 4095);
; #pragma unroll
;         for (int bj = 0; bj < 2; ++bj) {
;           const int colt = pn * 256 + bj * 128 + wc * 32;
;           f32x4 v0 = acc[ai][bj][m][0] * rsv, v1 = acc[ai][bj][m][1] * rsv;
;           bf16_t* zp = p.Z() + (size_t)row * LDZ + colt;
;           if (colt < 2048) {
;             const int ti = pos * 32 + 16 * (wc & 1) + 4 * fq;
;             const f32x4 c = *(const f32x4*)(p.cosT() + ti), s = *(const f32x4*)(p.sinT() + ti);
;             const float qs = (colt < 1024) ? 0.18033688011112042f : 1.f;
;             const f32x4 o0 = (v0 * c - v1 * s) * qs, o1 = (v1 * c + v0 * s) * qs;
;             const u32x4 w = {cvtpk(o0[0], o0[1]), cvtpk(o0[2], o0[3]), cvtpk(o1[0], o1[1]), cvtpk(o1[2], o1[3])};
;             *(u32x4*)(zp + 8 * fq) = w;
;           } else {
;             if (colt >= 3072) {
; #pragma unroll
;               for (int e = 0; e < 4; ++e) { v0[e] = gelu_tanh(v0[e]); v1[e] = gelu_tanh(v1[e]); }
;             }
;             const u32x4 w = {cvtpk(v0[0], v0[1]), cvtpk(v0[2], v0[3]), cvtpk(v1[0], v1[1]), cvtpk(v1[2], v1[3])};
;             *(u32x4*)(zp + 8 * fq) = w;
.LBB0_279:
	s_and_b64 vcc, exec, s[8:9]
	s_cbranch_vccz .LBB0_281
	v_mov_b64_e32 v[24:25], v[216:217]
	v_mov_b64_e32 v[26:27], v[218:219]
	v_mov_b64_e32 v[28:29], v[222:223]
	v_mov_b64_e32 v[30:31], v[224:225]
	s_cmpk_lt_i32 s21, 0x400
	s_cselect_b64 vcc, -1, 0
	v_cndmask_b32_e32 v32, 1.0, v220, vcc
	v_pk_mul_f32 v[34:35], v[18:19], v[26:27]
	v_pk_mul_f32 v[38:39], v[16:17], v[24:25]
	v_pk_mul_f32 v[26:27], v[22:23], v[26:27]
	v_pk_mul_f32 v[24:25], v[20:21], v[24:25]
	v_pk_fma_f32 v[22:23], v[22:23], v[30:31], v[34:35] neg_lo:[0,0,1] neg_hi:[0,0,1]
	v_pk_fma_f32 v[20:21], v[20:21], v[28:29], v[38:39] neg_lo:[0,0,1] neg_hi:[0,0,1]
	v_pk_fma_f32 v[18:19], v[18:19], v[30:31], v[26:27]
	v_pk_fma_f32 v[16:17], v[16:17], v[28:29], v[24:25]
	v_pk_mul_f32 v[22:23], v[32:33], v[22:23] op_sel_hi:[0,1]
	v_pk_mul_f32 v[20:21], v[32:33], v[20:21] op_sel_hi:[0,1]
	v_pk_mul_f32 v[18:19], v[32:33], v[18:19] op_sel_hi:[0,1]
	v_pk_mul_f32 v[16:17], v[32:33], v[16:17] op_sel_hi:[0,1]
	v_cvt_pk_bf16_f32 v24, v20, v21
	v_cvt_pk_bf16_f32 v25, v22, v23
	v_cvt_pk_bf16_f32 v26, v16, v17
	v_cvt_pk_bf16_f32 v27, v18, v19
.LBB0_281:
	v_add_u32_e32 v28, 0xb0, v146
	v_ashrrev_i32_e32 v29, 31, v28
	global_store_dwordx4 v[36:37], v[24:27], off offset:256
	v_lshl_add_u64 v[16:17], v[28:29], 2, s[12:13]
	s_and_b64 vcc, exec, s[4:5]
	v_cmp_gt_i32_e64 s[4:5], s2, v28
	s_mov_b64 s[8:9], -1
	v_mov_b32_e32 v26, v249
	v_pk_mul_f32 v[14:15], v[14:15], v[26:27] op_sel_hi:[1,0]
	v_pk_mul_f32 v[12:13], v[12:13], v[26:27] op_sel_hi:[1,0]
	v_pk_mul_f32 v[10:11], v[10:11], v[26:27] op_sel_hi:[1,0]
	v_pk_mul_f32 v[8:9], v[8:9], v[26:27] op_sel_hi:[1,0]
	s_cbranch_vccnz .LBB0_285
	v_mov_b64_e32 v[20:21], v[10:11]
	v_mov_b64_e32 v[24:25], v[14:15]
	s_cmpk_lt_u32 s1, 0xc00
	v_mov_b64_e32 v[18:19], v[8:9]
	v_mov_b64_e32 v[22:23], v[12:13]
	s_cbranch_scc1 .LBB0_284
	v_mul_f32_e32 v17, v8, v8
	v_fmamk_f32 v17, v17, 0x3dd2d3e8, v214
	v_mul_f32_e32 v18, v13, v13
	v_mul_f32_e64 v17, v8, -v17
	v_fmamk_f32 v18, v18, 0x3dd2d3e8, v214
	v_exp_f32_e32 v17, v17
	v_mul_f32_e64 v18, v13, -v18
	v_exp_f32_e32 v19, v18
	v_mul_f32_e32 v21, v10, v10
	v_add_f32_e32 v17, 1.0, v17
	v_mul_f32_e32 v16, v12, v12
	v_rcp_f32_e32 v18, v17
	v_add_f32_e32 v17, 1.0, v19
	v_mul_f32_e32 v19, v9, v9
	v_mul_f32_e32 v20, v14, v14
	v_fmamk_f32 v21, v21, 0x3dd2d3e8, v214
	v_mul_f32_e32 v22, v15, v15
	v_mul_f32_e32 v23, v11, v11
	v_fmamk_f32 v16, v16, 0x3dd2d3e8, v214
	v_fmamk_f32 v19, v19, 0x3dd2d3e8, v214
	v_fmamk_f32 v20, v20, 0x3dd2d3e8, v214
	v_mul_f32_e64 v21, v10, -v21
	v_fmamk_f32 v22, v22, 0x3dd2d3e8, v214
	v_fmamk_f32 v23, v23, 0x3dd2d3e8, v214
	v_mul_f32_e64 v16, v12, -v16
	v_mul_f32_e64 v19, v9, -v19
	v_mul_f32_e64 v20, v14, -v20
	v_exp_f32_e32 v21, v21
	v_mul_f32_e64 v22, v15, -v22
	v_mul_f32_e64 v23, v11, -v23
	v_exp_f32_e32 v16, v16
	v_exp_f32_e32 v19, v19
	v_exp_f32_e32 v20, v20
	v_exp_f32_e32 v22, v22
	v_exp_f32_e32 v23, v23
	v_add_f32_e32 v21, 1.0, v21
	v_add_f32_e32 v16, 1.0, v16
	v_add_f32_e32 v19, 1.0, v19
	v_add_f32_e32 v20, 1.0, v20
	v_rcp_f32_e32 v30, v21
	v_add_f32_e32 v21, 1.0, v22
	v_add_f32_e32 v22, 1.0, v23
	v_rcp_f32_e32 v16, v16
	v_rcp_f32_e32 v17, v17
	v_rcp_f32_e32 v20, v20
	v_rcp_f32_e32 v21, v21
	v_rcp_f32_e32 v31, v22
	v_rcp_f32_e32 v19, v19
	v_pk_mul_f32 v[22:23], v[12:13], v[16:17]
	v_pk_mul_f32 v[24:25], v[14:15], v[20:21]
	v_pk_mul_f32 v[20:21], v[10:11], v[30:31]
	v_pk_mul_f32 v[18:19], v[8:9], v[18:19]

;   __device__ __forceinline__ bf16_t* Z() const { return (bf16_t*)(ws + 456 * MB); }
;   __device__ __forceinline__ float* cosT() const { return (float*)(ws + 904 * MB); }
;   __device__ __forceinline__ float* sinT() const { return (float*)(ws + 905 * MB); }
; template <int MODE>
; __device__ __forceinline__ void gemm_epilogue(const Params& p, int layer, const f32x4 (&acc)[2][2][4][2], int pm, int pn, int wr, int wc, int fr, int fq) {
;     ...
;         const int pos = (row < NPROMPT) ? (row & 8191) : (row & 4095);
; #pragma unroll
;         for (int bj = 0; bj < 2; ++bj) {
;           const int colt = pn * 256 + bj * 128 + wc * 32;
;           f32x4 v0 = acc[ai][bj][m][0] * rsv, v1 = acc[ai][bj][m][1] * rsv;
;           bf16_t* zp = p.Z() + (size_t)row * LDZ + colt;
;           if (colt < 2048) {
;             const int ti = pos * 32 + 16 * (wc & 1) + 4 * fq;
;             const f32x4 c = *(const f32x4*)(p.cosT() + ti), s = *(const f32x4*)(p.sinT() + ti);
;             const float qs = (colt < 1024) ? 0.18033688011112042f : 1.f;
;             const f32x4 o0 = (v0 * c - v1 * s) * qs, o1 = (v1 * c + v0 * s) * qs;
;             const u32x4 w = {cvtpk(o0[0], o0[1]), cvtpk(o0[2], o0[3]), cvtpk(o1[0], o1[1]), cvtpk(o1[2], o1[3])};
;             *(u32x4*)(zp + 8 * fq) = w;
.LBB0_285:
	v_cndmask_b32_e64 v20, v240, v241, s[4:5]
	v_and_b32_e32 v20, v20, v28
	v_lshl_or_b32 v20, v20, 5, v153
	s_and_b64 vcc, exec, s[8:9]
	v_lshlrev_b32_e32 v22, 2, v20
	s_cbranch_vccz .LBB0_287
	global_load_dwordx4 v[16:19], v22, s[18:19]
	global_load_dwordx4 v[30:33], v22, s[16:17]
	s_cmpk_lt_i32 s46, 0x400
	s_cselect_b64 vcc, -1, 0
	v_cndmask_b32_e32 v20, 1.0, v220, vcc
	s_waitcnt vmcnt(0)
	v_mov_b64_e32 v[216:217], v[16:17]
	v_mov_b64_e32 v[218:219], v[18:19]
	v_mov_b64_e32 v[222:223], v[30:31]
	v_mov_b64_e32 v[224:225], v[32:33]
	v_pk_mul_f32 v[24:25], v[10:11], v[18:19]
	v_pk_mul_f32 v[34:35], v[8:9], v[16:17]
	v_pk_mul_f32 v[18:19], v[14:15], v[18:19]
	v_pk_mul_f32 v[16:17], v[12:13], v[16:17]
	v_pk_fma_f32 v[14:15], v[14:15], v[32:33], v[24:25] neg_lo:[0,0,1] neg_hi:[0,0,1]
	v_pk_fma_f32 v[12:13], v[12:13], v[30:31], v[34:35] neg_lo:[0,0,1] neg_hi:[0,0,1]
	v_pk_fma_f32 v[10:11], v[10:11], v[32:33], v[18:19]
	v_pk_fma_f32 v[8:9], v[8:9], v[30:31], v[16:17]
	v_pk_mul_f32 v[14:15], v[20:21], v[14:15] op_sel_hi:[0,1]
	v_pk_mul_f32 v[12:13], v[20:21], v[12:13] op_sel_hi:[0,1]
	v_pk_mul_f32 v[10:11], v[20:21], v[10:11] op_sel_hi:[0,1]
	v_pk_mul_f32 v[8:9], v[20:21], v[8:9] op_sel_hi:[0,1]
	v_cvt_pk_bf16_f32 v16, v12, v13
	v_cvt_pk_bf16_f32 v17, v14, v15
	v_cvt_pk_bf16_f32 v18, v8, v9
	v_cvt_pk_bf16_f32 v19, v10, v11

;   __device__ __forceinline__ bf16_t* Z() const { return (bf16_t*)(ws + 456 * MB); }
;   __device__ __forceinline__ float* cosT() const { return (float*)(ws + 904 * MB); }
;   __device__ __forceinline__ float* sinT() const { return (float*)(ws + 905 * MB); }
; template <int MODE>
; __device__ __forceinline__ void gemm_epilogue(const Params& p, int layer, const f32x4 (&acc)[2][2][4][2], int pm, int pn, int wr, int wc, int fr, int fq) {
;     ...
;           f32x4 v0 = acc[ai][bj][m][0] * rsv, v1 = acc[ai][bj][m][1] * rsv;
;           bf16_t* zp = p.Z() + (size_t)row * LDZ + colt;
;           if (colt < 2048) {
;             const int ti = pos * 32 + 16 * (wc & 1) + 4 * fq;
;             const f32x4 c = *(const f32x4*)(p.cosT() + ti), s = *(const f32x4*)(p.sinT() + ti);
;             const float qs = (colt < 1024) ? 0.18033688011112042f : 1.f;
;             const f32x4 o0 = (v0 * c - v1 * s) * qs, o1 = (v1 * c + v0 * s) * qs;
;             const u32x4 w = {cvtpk(o0[0], o0[1]), cvtpk(o0[2], o0[3]), cvtpk(o1[0], o1[1]), cvtpk(o1[2], o1[3])};
;             *(u32x4*)(zp + 8 * fq) = w;
.LBB0_291:
	s_and_b64 vcc, exec, s[4:5]
	s_cbranch_vccz .LBB0_192
	v_mov_b64_e32 v[8:9], v[216:217]
	v_mov_b64_e32 v[10:11], v[218:219]
	v_mov_b64_e32 v[12:13], v[222:223]
	v_mov_b64_e32 v[14:15], v[224:225]
	s_cmpk_lt_i32 s21, 0x400
	s_cselect_b64 vcc, -1, 0
	v_cndmask_b32_e32 v16, 1.0, v220, vcc
	v_pk_mul_f32 v[18:19], v[2:3], v[10:11]
	v_pk_mul_f32 v[22:23], v[0:1], v[8:9]
	v_pk_mul_f32 v[10:11], v[6:7], v[10:11]
	v_pk_mul_f32 v[8:9], v[4:5], v[8:9]
	v_pk_fma_f32 v[6:7], v[6:7], v[14:15], v[18:19] neg_lo:[0,0,1] neg_hi:[0,0,1]
	v_pk_fma_f32 v[4:5], v[4:5], v[12:13], v[22:23] neg_lo:[0,0,1] neg_hi:[0,0,1]
	v_pk_fma_f32 v[2:3], v[2:3], v[14:15], v[10:11]
	v_pk_fma_f32 v[0:1], v[0:1], v[12:13], v[8:9]
	v_pk_mul_f32 v[6:7], v[16:17], v[6:7] op_sel_hi:[0,1]
	v_pk_mul_f32 v[4:5], v[16:17], v[4:5] op_sel_hi:[0,1]
	v_pk_mul_f32 v[2:3], v[16:17], v[2:3] op_sel_hi:[0,1]
	v_pk_mul_f32 v[0:1], v[16:17], v[0:1] op_sel_hi:[0,1]
	v_cvt_pk_bf16_f32 v8, v4, v5
	v_cvt_pk_bf16_f32 v9, v6, v7
	v_cvt_pk_bf16_f32 v10, v0, v1
	v_cvt_pk_bf16_f32 v11, v2, v3
	s_branch .LBB0_192
